# v8 + hyena FFT load loops (conv 2x8K/16K, filter-spectrum 8K/16K) fully unrolled with run-ahead global loads kept in flight
# speedup vs baseline: 1.0063x; 1.0063x over previous
; DI float2 twid(float r) { return float2{__builtin_amdgcn_cosf(r), -__builtin_amdgcn_sinf(r)}; }
; template <int LOGN> DI void filtfft_item(const Params& p, int ch, int cc, const float* kr, float2* kh) {
;   constexpr int N = 1 << LOGN; int tid = threadIdx.x; asm volatile("" : "+v"(tid)); float2* z = (float2*)smem; float* redbuf = (float*)(smem + 131072);
;   float ss = 0.f;
;   if constexpr (LOGN & 1) {
;     for (int i = tid; i < N / 2; i += NTHR) { float k0 = kr[i], k1 = kr[i + N / 2]; ss += k0 * k0 + k1 * k1; float2 w = twid((float)i * (1.f / N)); float d = k0 - k1;
;       z[i] = float2{k0 + k1, 0.f}; z[i + N / 2] = float2{d * w.x, d * w.y}; }
.LBB0_1484:
	v_mov_b32_e32 v218, v2
	v_mov_b32_e32 v219, v3
	v_add_co_u32_e32 v220, vcc, 0xffffc000, v218
	s_nop 1
	v_addc_co_u32_e32 v221, vcc, -1, v219, vcc
	global_load_dword v222, v[220:221], off
	global_load_dword v223, v[218:219], off
	v_lshl_add_u64 v[218:219], v[218:219], 0, s[6:7]
	v_add_co_u32_e32 v220, vcc, 0xffffc000, v218
	s_nop 1
	v_addc_co_u32_e32 v221, vcc, -1, v219, vcc
	global_load_dword v224, v[220:221], off
	global_load_dword v225, v[218:219], off
	v_lshl_add_u64 v[218:219], v[218:219], 0, s[6:7]
	v_add_co_u32_e32 v220, vcc, 0xffffc000, v218
	s_nop 1
	v_addc_co_u32_e32 v221, vcc, -1, v219, vcc
	global_load_dword v226, v[220:221], off
	global_load_dword v227, v[218:219], off
	v_lshl_add_u64 v[218:219], v[218:219], 0, s[6:7]
	v_add_co_u32_e32 v220, vcc, 0xffffc000, v218
	s_nop 1
	v_addc_co_u32_e32 v221, vcc, -1, v219, vcc
	global_load_dword v228, v[220:221], off
	global_load_dword v229, v[218:219], off
	v_lshl_add_u64 v[218:219], v[218:219], 0, s[6:7]
	v_add_co_u32_e32 v220, vcc, 0xffffc000, v218
	s_nop 1
	v_addc_co_u32_e32 v221, vcc, -1, v219, vcc
	global_load_dword v230, v[220:221], off
	global_load_dword v231, v[218:219], off
	v_lshl_add_u64 v[218:219], v[218:219], 0, s[6:7]
	v_add_co_u32_e32 v220, vcc, 0xffffc000, v218
	s_nop 1
	v_addc_co_u32_e32 v221, vcc, -1, v219, vcc
	global_load_dword v232, v[220:221], off
	global_load_dword v233, v[218:219], off
	v_lshl_add_u64 v[218:219], v[218:219], 0, s[6:7]
	v_add_co_u32_e32 v220, vcc, 0xffffc000, v218
	s_nop 1
	v_addc_co_u32_e32 v221, vcc, -1, v219, vcc
	global_load_dword v234, v[220:221], off
	global_load_dword v235, v[218:219], off
	v_lshl_add_u64 v[218:219], v[218:219], 0, s[6:7]
	v_add_co_u32_e32 v220, vcc, 0xffffc000, v218
	s_nop 1
	v_addc_co_u32_e32 v221, vcc, -1, v219, vcc
	global_load_dword v236, v[220:221], off
	global_load_dword v237, v[218:219], off
	v_lshl_add_u64 v[218:219], v[218:219], 0, s[6:7]
	v_add_co_u32_e32 v8, vcc, 0xffffc000, v2
	s_nop 1
	v_addc_co_u32_e32 v9, vcc, -1, v3, vcc
	s_nop 0
	v_lshl_add_u64 v[2:3], v[2:3], 0, s[6:7]
	s_nop 0
	s_waitcnt vmcnt(14)
	v_mov_b32_e32 v8, v222
	v_mov_b32_e32 v9, v223
	v_pk_mul_f32 v[12:13], v[8:9], v[8:9]
	s_nop 0
	v_add_f32_e32 v0, v12, v13
	v_add_f32_e32 v4, v4, v0
	v_cvt_f32_i32_e32 v0, v6
	v_sub_f32_e32 v14, v8, v9
	v_mul_f32_e32 v0, 0x39000000, v0
	v_cos_f32_e32 v12, v0
	v_sin_f32_e64 v13, -v0
	v_add_f32_e32 v0, v8, v9
	v_pk_mul_f32 v[8:9], v[12:13], v[14:15] op_sel_hi:[1,0]
	ds_write2st64_b64 v5, v[0:1], v[8:9] offset1:64
	v_add_u32_e32 v0, 0x200, v6
	v_add_u32_e32 v5, 0x1000, v5
	v_mov_b32_e32 v6, v0
	s_nop 0
	v_add_co_u32_e32 v8, vcc, 0xffffc000, v2
	s_nop 1
	v_addc_co_u32_e32 v9, vcc, -1, v3, vcc
	s_nop 0
	v_lshl_add_u64 v[2:3], v[2:3], 0, s[6:7]
	s_nop 0
	s_waitcnt vmcnt(12)
	v_mov_b32_e32 v8, v224
	v_mov_b32_e32 v9, v225
	v_pk_mul_f32 v[12:13], v[8:9], v[8:9]
	s_nop 0
	v_add_f32_e32 v0, v12, v13
	v_add_f32_e32 v4, v4, v0
	v_cvt_f32_i32_e32 v0, v6
	v_sub_f32_e32 v14, v8, v9
	v_mul_f32_e32 v0, 0x39000000, v0
	v_cos_f32_e32 v12, v0
	v_sin_f32_e64 v13, -v0
	v_add_f32_e32 v0, v8, v9
	v_pk_mul_f32 v[8:9], v[12:13], v[14:15] op_sel_hi:[1,0]
	ds_write2st64_b64 v5, v[0:1], v[8:9] offset1:64
	v_add_u32_e32 v0, 0x200, v6
	v_add_u32_e32 v5, 0x1000, v5
	v_mov_b32_e32 v6, v0
	s_nop 0
	v_add_co_u32_e32 v8, vcc, 0xffffc000, v2
	s_nop 1
	v_addc_co_u32_e32 v9, vcc, -1, v3, vcc
	s_nop 0
	v_lshl_add_u64 v[2:3], v[2:3], 0, s[6:7]
	s_nop 0
	s_waitcnt vmcnt(10)
; DI float2 twid(float r) { return float2{__builtin_amdgcn_cosf(r), -__builtin_amdgcn_sinf(r)}; }
; template <int LOGN> DI void filtfft_item(const Params& p, int ch, int cc, const float* kr, float2* kh) {
;     ...
;     for (int i = tid; i < N / 2; i += NTHR) { float k0 = kr[i], k1 = kr[i + N / 2]; ss += k0 * k0 + k1 * k1; float2 w = twid((float)i * (1.f / N)); float d = k0 - k1;
;       z[i] = float2{k0 + k1, 0.f}; z[i + N / 2] = float2{d * w.x, d * w.y}; }
	v_mov_b32_e32 v8, v226
	v_mov_b32_e32 v9, v227
	v_pk_mul_f32 v[12:13], v[8:9], v[8:9]
	s_nop 0
	v_add_f32_e32 v0, v12, v13
	v_add_f32_e32 v4, v4, v0
	v_cvt_f32_i32_e32 v0, v6
	v_sub_f32_e32 v14, v8, v9
	v_mul_f32_e32 v0, 0x39000000, v0
	v_cos_f32_e32 v12, v0
	v_sin_f32_e64 v13, -v0
	v_add_f32_e32 v0, v8, v9
	v_pk_mul_f32 v[8:9], v[12:13], v[14:15] op_sel_hi:[1,0]
	ds_write2st64_b64 v5, v[0:1], v[8:9] offset1:64
	v_add_u32_e32 v0, 0x200, v6
	v_add_u32_e32 v5, 0x1000, v5
	v_mov_b32_e32 v6, v0
	s_nop 0
	v_add_co_u32_e32 v8, vcc, 0xffffc000, v2
	s_nop 1
	v_addc_co_u32_e32 v9, vcc, -1, v3, vcc
	s_nop 0
	v_lshl_add_u64 v[2:3], v[2:3], 0, s[6:7]
	s_nop 0
	s_waitcnt vmcnt(8)
	v_mov_b32_e32 v8, v228
	v_mov_b32_e32 v9, v229
	v_pk_mul_f32 v[12:13], v[8:9], v[8:9]
	s_nop 0
	v_add_f32_e32 v0, v12, v13
	v_add_f32_e32 v4, v4, v0
	v_cvt_f32_i32_e32 v0, v6
	v_sub_f32_e32 v14, v8, v9
	v_mul_f32_e32 v0, 0x39000000, v0
	v_cos_f32_e32 v12, v0
	v_sin_f32_e64 v13, -v0
	v_add_f32_e32 v0, v8, v9
	v_pk_mul_f32 v[8:9], v[12:13], v[14:15] op_sel_hi:[1,0]
	ds_write2st64_b64 v5, v[0:1], v[8:9] offset1:64
	v_add_u32_e32 v0, 0x200, v6
	v_add_u32_e32 v5, 0x1000, v5
	v_mov_b32_e32 v6, v0
	s_nop 0
	v_add_co_u32_e32 v8, vcc, 0xffffc000, v2
	s_nop 1
	v_addc_co_u32_e32 v9, vcc, -1, v3, vcc
	s_nop 0
	v_lshl_add_u64 v[2:3], v[2:3], 0, s[6:7]
	s_nop 0
	s_waitcnt vmcnt(6)
	v_mov_b32_e32 v8, v230
	v_mov_b32_e32 v9, v231
	v_pk_mul_f32 v[12:13], v[8:9], v[8:9]
	s_nop 0
	v_add_f32_e32 v0, v12, v13
	v_add_f32_e32 v4, v4, v0
	v_cvt_f32_i32_e32 v0, v6
	v_sub_f32_e32 v14, v8, v9
	v_mul_f32_e32 v0, 0x39000000, v0
	v_cos_f32_e32 v12, v0
	v_sin_f32_e64 v13, -v0
	v_add_f32_e32 v0, v8, v9
	v_pk_mul_f32 v[8:9], v[12:13], v[14:15] op_sel_hi:[1,0]
	ds_write2st64_b64 v5, v[0:1], v[8:9] offset1:64
	v_add_u32_e32 v0, 0x200, v6
	v_add_u32_e32 v5, 0x1000, v5
	v_mov_b32_e32 v6, v0
	s_nop 0
	v_add_co_u32_e32 v8, vcc, 0xffffc000, v2
	s_nop 1
	v_addc_co_u32_e32 v9, vcc, -1, v3, vcc
	s_nop 0
	v_lshl_add_u64 v[2:3], v[2:3], 0, s[6:7]
	s_nop 0
	s_waitcnt vmcnt(4)
	v_mov_b32_e32 v8, v232
	v_mov_b32_e32 v9, v233
	v_pk_mul_f32 v[12:13], v[8:9], v[8:9]
	s_nop 0
	v_add_f32_e32 v0, v12, v13
	v_add_f32_e32 v4, v4, v0
	v_cvt_f32_i32_e32 v0, v6
	v_sub_f32_e32 v14, v8, v9
	v_mul_f32_e32 v0, 0x39000000, v0
	v_cos_f32_e32 v12, v0
	v_sin_f32_e64 v13, -v0
	v_add_f32_e32 v0, v8, v9
	v_pk_mul_f32 v[8:9], v[12:13], v[14:15] op_sel_hi:[1,0]
	ds_write2st64_b64 v5, v[0:1], v[8:9] offset1:64
	v_add_u32_e32 v0, 0x200, v6
	v_add_u32_e32 v5, 0x1000, v5
	v_mov_b32_e32 v6, v0
	s_nop 0
	v_add_co_u32_e32 v8, vcc, 0xffffc000, v2
	s_nop 1
	v_addc_co_u32_e32 v9, vcc, -1, v3, vcc
	s_nop 0
	v_lshl_add_u64 v[2:3], v[2:3], 0, s[6:7]
	s_nop 0
	s_waitcnt vmcnt(2)
	v_mov_b32_e32 v8, v234
	v_mov_b32_e32 v9, v235
	v_pk_mul_f32 v[12:13], v[8:9], v[8:9]
	s_nop 0
	v_add_f32_e32 v0, v12, v13
	v_add_f32_e32 v4, v4, v0
	v_cvt_f32_i32_e32 v0, v6
	v_sub_f32_e32 v14, v8, v9
	v_mul_f32_e32 v0, 0x39000000, v0
	v_cos_f32_e32 v12, v0
	v_sin_f32_e64 v13, -v0
	v_add_f32_e32 v0, v8, v9
	v_pk_mul_f32 v[8:9], v[12:13], v[14:15] op_sel_hi:[1,0]
	ds_write2st64_b64 v5, v[0:1], v[8:9] offset1:64
	v_add_u32_e32 v0, 0x200, v6
	v_add_u32_e32 v5, 0x1000, v5
	v_mov_b32_e32 v6, v0
	s_nop 0
	v_add_co_u32_e32 v8, vcc, 0xffffc000, v2
	s_nop 1
	v_addc_co_u32_e32 v9, vcc, -1, v3, vcc
	s_nop 0
	v_lshl_add_u64 v[2:3], v[2:3], 0, s[6:7]
	s_nop 0
	s_waitcnt vmcnt(0)
	v_mov_b32_e32 v8, v236
	v_mov_b32_e32 v9, v237
	v_pk_mul_f32 v[12:13], v[8:9], v[8:9]
	s_nop 0
	v_add_f32_e32 v0, v12, v13
	v_add_f32_e32 v4, v4, v0
	v_cvt_f32_i32_e32 v0, v6
	v_sub_f32_e32 v14, v8, v9
	v_mul_f32_e32 v0, 0x39000000, v0
	v_cos_f32_e32 v12, v0
	v_sin_f32_e64 v13, -v0
	v_add_f32_e32 v0, v8, v9
	v_pk_mul_f32 v[8:9], v[12:13], v[14:15] op_sel_hi:[1,0]
	ds_write2st64_b64 v5, v[0:1], v[8:9] offset1:64
	v_add_u32_e32 v0, 0x200, v6
	v_add_u32_e32 v5, 0x1000, v5
	v_mov_b32_e32 v6, v0
	s_nop 0
	s_mov_b64 s[8:9], exec
	s_or_b64 exec, exec, s[8:9]

; DI float2 twid(float r) { return float2{__builtin_amdgcn_cosf(r), -__builtin_amdgcn_sinf(r)}; }
; DI void bfly_fwd(float2 a0, float2 a1, float2 a2, float2 a3, float r, float2& o0, float2& o1, float2& o2, float2& o3) {
;   float2 t0 = {a0.x + a2.x, a0.y + a2.y}, t1 = {a0.x - a2.x, a0.y - a2.y}, t2 = {a1.x + a3.x, a1.y + a3.y}, t3 = {a1.x - a3.x, a1.y - a3.y};
;   float2 b0 = {t0.x + t2.x, t0.y + t2.y}, b2 = {t0.x - t2.x, t0.y - t2.y}, b1 = {t1.x + t3.y, t1.y - t3.x}, b3 = {t1.x - t3.y, t1.y + t3.x};
;   float2 w1 = twid(r), w2 = cmul(w1, w1), w3 = cmul(w2, w1);
;   o0 = b0; o1 = cmul(b1, w1); o2 = cmul(b2, w2); o3 = cmul(b3, w3);
; }
; template <int LOGN> DI void filtfft_item(const Params& p, int ch, int cc, const float* kr, float2* kh) {
;     ...
;     constexpr int Q = N / 4;
;     for (int i = tid; i < Q; i += NTHR) { float k0 = kr[i], k1 = kr[i + Q], k2 = kr[i + 2 * Q], k3 = kr[i + 3 * Q]; ss += k0 * k0 + k1 * k1 + k2 * k2 + k3 * k3; float2 o0, o1, o2, o3;
;       bfly_fwd(float2{k0, 0.f}, float2{k1, 0.f}, float2{k2, 0.f}, float2{k3, 0.f}, (float)i * (1.f / N), o0, o1, o2, o3);
;       z[i] = o0; z[i + Q] = o1; z[i + 2 * Q] = o2; z[i + 3 * Q] = o3; }
.LBB0_1512:
	v_mov_b32_e32 v218, v2
	v_mov_b32_e32 v219, v3
	v_add_co_u32_e32 v220, vcc, 0xffff4000, v218
	s_nop 1
	v_addc_co_u32_e32 v221, vcc, -1, v219, vcc
	v_add_co_u32_e32 v222, vcc, 0xffff8000, v218
	global_load_dword v224, v[220:221], off
	s_nop 0
	v_addc_co_u32_e32 v223, vcc, -1, v219, vcc
	global_load_dword v225, v[222:223], off
	v_add_co_u32_e32 v222, vcc, 0xffffc000, v218
	s_nop 1
	v_addc_co_u32_e32 v223, vcc, -1, v219, vcc
	global_load_dword v226, v[222:223], off
	global_load_dword v227, v[218:219], off
	v_lshl_add_u64 v[218:219], v[218:219], 0, s[6:7]
	v_add_co_u32_e32 v220, vcc, 0xffff4000, v218
	s_nop 1
	v_addc_co_u32_e32 v221, vcc, -1, v219, vcc
	v_add_co_u32_e32 v222, vcc, 0xffff8000, v218
	global_load_dword v228, v[220:221], off
	s_nop 0
	v_addc_co_u32_e32 v223, vcc, -1, v219, vcc
	global_load_dword v229, v[222:223], off
	v_add_co_u32_e32 v222, vcc, 0xffffc000, v218
	s_nop 1
	v_addc_co_u32_e32 v223, vcc, -1, v219, vcc
	global_load_dword v230, v[222:223], off
	global_load_dword v231, v[218:219], off
	v_lshl_add_u64 v[218:219], v[218:219], 0, s[6:7]
	v_add_co_u32_e32 v220, vcc, 0xffff4000, v218
	s_nop 1
	v_addc_co_u32_e32 v221, vcc, -1, v219, vcc
	v_add_co_u32_e32 v222, vcc, 0xffff8000, v218
	global_load_dword v232, v[220:221], off
	s_nop 0
	v_addc_co_u32_e32 v223, vcc, -1, v219, vcc
	global_load_dword v233, v[222:223], off
	v_add_co_u32_e32 v222, vcc, 0xffffc000, v218
	s_nop 1
	v_addc_co_u32_e32 v223, vcc, -1, v219, vcc
	global_load_dword v234, v[222:223], off
	global_load_dword v235, v[218:219], off
	v_lshl_add_u64 v[218:219], v[218:219], 0, s[6:7]
	v_add_co_u32_e32 v220, vcc, 0xffff4000, v218
	s_nop 1
	v_addc_co_u32_e32 v221, vcc, -1, v219, vcc
	v_add_co_u32_e32 v222, vcc, 0xffff8000, v218
	global_load_dword v236, v[220:221], off
	s_nop 0
	v_addc_co_u32_e32 v223, vcc, -1, v219, vcc
	global_load_dword v237, v[222:223], off
	v_add_co_u32_e32 v222, vcc, 0xffffc000, v218
	s_nop 1
	v_addc_co_u32_e32 v223, vcc, -1, v219, vcc
	global_load_dword v238, v[222:223], off
	global_load_dword v239, v[218:219], off
	v_lshl_add_u64 v[218:219], v[218:219], 0, s[6:7]
	v_add_co_u32_e32 v220, vcc, 0xffff4000, v218
	s_nop 1
	v_addc_co_u32_e32 v221, vcc, -1, v219, vcc
	v_add_co_u32_e32 v222, vcc, 0xffff8000, v218
	global_load_dword v241, v[220:221], off
	s_nop 0
	v_addc_co_u32_e32 v223, vcc, -1, v219, vcc
	global_load_dword v242, v[222:223], off
	v_add_co_u32_e32 v222, vcc, 0xffffc000, v218
	s_nop 1
	v_addc_co_u32_e32 v223, vcc, -1, v219, vcc
	global_load_dword v243, v[222:223], off
	global_load_dword v244, v[218:219], off
	v_lshl_add_u64 v[218:219], v[218:219], 0, s[6:7]
	v_add_co_u32_e32 v220, vcc, 0xffff4000, v218
	s_nop 1
	v_addc_co_u32_e32 v221, vcc, -1, v219, vcc
	v_add_co_u32_e32 v222, vcc, 0xffff8000, v218
	global_load_dword v245, v[220:221], off
	s_nop 0
	v_addc_co_u32_e32 v223, vcc, -1, v219, vcc
	global_load_dword v246, v[222:223], off
	v_add_co_u32_e32 v222, vcc, 0xffffc000, v218
	s_nop 1
	v_addc_co_u32_e32 v223, vcc, -1, v219, vcc
	global_load_dword v247, v[222:223], off
	global_load_dword v248, v[218:219], off
	v_lshl_add_u64 v[218:219], v[218:219], 0, s[6:7]
	v_add_co_u32_e32 v220, vcc, 0xffff4000, v218
	s_nop 1
	v_addc_co_u32_e32 v221, vcc, -1, v219, vcc
	v_add_co_u32_e32 v222, vcc, 0xffff8000, v218
	global_load_dword v249, v[220:221], off
	s_nop 0
	v_addc_co_u32_e32 v223, vcc, -1, v219, vcc
	global_load_dword v250, v[222:223], off
	v_add_co_u32_e32 v222, vcc, 0xffffc000, v218
	s_nop 1
	v_addc_co_u32_e32 v223, vcc, -1, v219, vcc
	global_load_dword v251, v[222:223], off
	global_load_dword v252, v[218:219], off
	v_lshl_add_u64 v[218:219], v[218:219], 0, s[6:7]
	v_add_co_u32_e32 v8, vcc, 0xffff4000, v2
	s_nop 1
	v_addc_co_u32_e32 v9, vcc, -1, v3, vcc
	v_add_co_u32_e32 v12, vcc, 0xffff8000, v2
	s_nop 0
	v_addc_co_u32_e32 v13, vcc, -1, v3, vcc
	s_nop 0
	v_add_co_u32_e32 v12, vcc, 0xffffc000, v2
	s_waitcnt vmcnt(26)
	v_mov_b32_e32 v8, v224
	v_mov_b32_e32 v9, v225
	v_pk_mul_f32 v[14:15], v[8:9], v[8:9]
	v_addc_co_u32_e32 v13, vcc, -1, v3, vcc
	s_nop 0
	v_add_f32_e32 v0, v14, v15
	s_nop 0
	v_lshl_add_u64 v[2:3], v[2:3], 0, s[6:7]
	s_nop 0
	s_waitcnt vmcnt(24)
	v_mov_b32_e32 v12, v226
	v_mov_b32_e32 v13, v227
	v_pk_mul_f32 v[16:17], v[12:13], v[12:13]
	s_nop 0
	v_add_f32_e32 v0, v0, v16
	v_add_f32_e32 v0, v0, v17
	v_add_f32_e32 v4, v4, v0
	v_cvt_f32_i32_e32 v0, v6
	v_pk_add_f32 v[14:15], v[8:9], v[12:13]
	v_pk_add_f32 v[8:9], v[8:9], v[12:13] neg_lo:[0,1] neg_hi:[0,1]
	v_mul_f32_e32 v7, 0x38800000, v0
	v_sin_f32_e32 v18, v7
	v_cos_f32_e32 v16, v7
	v_pk_add_f32 v[12:13], v[8:9], 0 op_sel_hi:[1,0]
	v_pk_add_f32 v[20:21], v[8:9], 0 op_sel_hi:[1,0] neg_lo:[1,0] neg_hi:[1,0]
	v_xor_b32_e32 v17, 0x80000000, v18
	v_mov_b32_e32 v23, v21
	v_pk_mov_b32 v[20:21], v[20:21], v[12:13] op_sel:[1,0]
	v_mov_b32_e32 v22, v12
	v_pk_mul_f32 v[20:21], v[18:19], v[20:21] op_sel_hi:[0,1]
	s_nop 0
	v_pk_fma_f32 v[12:13], v[16:17], v[12:13], v[20:21]
	v_pk_fma_f32 v[20:21], v[16:17], v[22:23], v[20:21] op_sel_hi:[0,1,1] neg_lo:[0,0,1] neg_hi:[0,0,1]
	v_add_f32_e32 v0, v14, v15
	v_mov_b32_e32 v13, v21
	ds_write2st64_b64 v5, v[0:1], v[12:13] offset1:64
	v_mov_b32_e32 v19, v16
	v_mov_b32_e32 v12, v18
	v_mov_b32_e32 v13, v17
	v_pk_mul_f32 v[12:13], v[18:19], v[12:13]
	v_pk_add_f32 v[14:15], v[14:15], v[14:15] op_sel:[0,1] op_sel_hi:[0,1] neg_lo:[0,1] neg_hi:[0,1]
	v_pk_fma_f32 v[20:21], v[16:17], v[16:17], v[12:13] op_sel_hi:[0,1,1] neg_lo:[0,0,1] neg_hi:[0,0,1]
	v_pk_fma_f32 v[12:13], v[16:17], v[16:17], v[12:13] op_sel_hi:[0,1,1]
	s_nop 0
	v_mov_b32_e32 v23, v13
	v_pk_mov_b32 v[12:13], v[12:13], v[20:21] op_sel:[1,0]
	v_mov_b32_e32 v22, v20
; DI float2 twid(float r) { return float2{__builtin_amdgcn_cosf(r), -__builtin_amdgcn_sinf(r)}; }
; DI void bfly_fwd(float2 a0, float2 a1, float2 a2, float2 a3, float r, float2& o0, float2& o1, float2& o2, float2& o3) {
;   float2 t0 = {a0.x + a2.x, a0.y + a2.y}, t1 = {a0.x - a2.x, a0.y - a2.y}, t2 = {a1.x + a3.x, a1.y + a3.y}, t3 = {a1.x - a3.x, a1.y - a3.y};
;   float2 b0 = {t0.x + t2.x, t0.y + t2.y}, b2 = {t0.x - t2.x, t0.y - t2.y}, b1 = {t1.x + t3.y, t1.y - t3.x}, b3 = {t1.x - t3.y, t1.y + t3.x};
;   float2 w1 = twid(r), w2 = cmul(w1, w1), w3 = cmul(w2, w1);
;   o0 = b0; o1 = cmul(b1, w1); o2 = cmul(b2, w2); o3 = cmul(b3, w3);
; }
; template <int LOGN> DI void filtfft_item(const Params& p, int ch, int cc, const float* kr, float2* kh) {
;     ...
;     constexpr int Q = N / 4;
;     for (int i = tid; i < Q; i += NTHR) { float k0 = kr[i], k1 = kr[i + Q], k2 = kr[i + 2 * Q], k3 = kr[i + 3 * Q]; ss += k0 * k0 + k1 * k1 + k2 * k2 + k3 * k3; float2 o0, o1, o2, o3;
;       bfly_fwd(float2{k0, 0.f}, float2{k1, 0.f}, float2{k2, 0.f}, float2{k3, 0.f}, (float)i * (1.f / N), o0, o1, o2, o3);
;       z[i] = o0; z[i + Q] = o1; z[i + 2 * Q] = o2; z[i + 3 * Q] = o3; }
	v_pk_mul_f32 v[12:13], v[12:13], 0 op_sel_hi:[1,0]
	v_add_f32_e32 v24, 0, v9
	v_pk_fma_f32 v[20:21], v[20:21], v[14:15], v[12:13] neg_lo:[0,0,1] neg_hi:[0,0,1]
	v_pk_fma_f32 v[12:13], v[22:23], v[14:15], v[12:13]
	v_add_u32_e32 v0, 0x10000, v5
	v_mov_b32_e32 v21, v13
	v_pk_mul_f32 v[12:13], v[18:19], v[22:23] op_sel_hi:[0,1]
	s_nop 0
	v_pk_fma_f32 v[14:15], v[16:17], v[22:23], v[12:13] op_sel:[0,0,1] op_sel_hi:[0,1,0]
	v_pk_fma_f32 v[12:13], v[16:17], v[22:23], v[12:13] op_sel:[0,0,1] op_sel_hi:[0,1,0] neg_lo:[0,0,1] neg_hi:[0,0,1]
	s_nop 0
	v_mov_b32_e32 v17, v13
	v_pk_mov_b32 v[12:13], v[12:13], v[14:15] op_sel:[1,0]
	v_mov_b32_e32 v16, v14
	v_pk_mul_f32 v[12:13], v[24:25], v[12:13] op_sel_hi:[0,1]
	s_nop 0
	v_pk_fma_f32 v[14:15], v[8:9], v[14:15], v[12:13] neg_lo:[0,0,1] neg_hi:[0,0,1]
	v_pk_fma_f32 v[8:9], v[8:9], v[16:17], v[12:13] op_sel_hi:[0,1,1]
	ds_write_b64 v0, v[20:21]
	v_add_u32_e32 v0, 0x18000, v5
	v_mov_b32_e32 v15, v9
	ds_write_b64 v0, v[14:15]
	v_add_u32_e32 v0, 0x200, v6
	v_add_u32_e32 v5, 0x1000, v5
	v_mov_b32_e32 v6, v0
	s_nop 0
	v_add_co_u32_e32 v220, vcc, 0xffff4000, v218
	s_nop 1
	v_addc_co_u32_e32 v221, vcc, -1, v219, vcc
	v_add_co_u32_e32 v222, vcc, 0xffff8000, v218
	global_load_dword v224, v[220:221], off
	s_nop 0
	v_addc_co_u32_e32 v223, vcc, -1, v219, vcc
	global_load_dword v225, v[222:223], off
	v_add_co_u32_e32 v222, vcc, 0xffffc000, v218
	s_nop 1
	v_addc_co_u32_e32 v223, vcc, -1, v219, vcc
	global_load_dword v226, v[222:223], off
	global_load_dword v227, v[218:219], off
	v_lshl_add_u64 v[218:219], v[218:219], 0, s[6:7]
	v_add_co_u32_e32 v8, vcc, 0xffff4000, v2
	s_nop 1
	v_addc_co_u32_e32 v9, vcc, -1, v3, vcc
	v_add_co_u32_e32 v12, vcc, 0xffff8000, v2
	s_nop 0
	v_addc_co_u32_e32 v13, vcc, -1, v3, vcc
	s_nop 0
	v_add_co_u32_e32 v12, vcc, 0xffffc000, v2
	s_waitcnt vmcnt(26)
	v_mov_b32_e32 v8, v228
	v_mov_b32_e32 v9, v229
	v_pk_mul_f32 v[14:15], v[8:9], v[8:9]
	v_addc_co_u32_e32 v13, vcc, -1, v3, vcc
	s_nop 0
	v_add_f32_e32 v0, v14, v15
	s_nop 0
	v_lshl_add_u64 v[2:3], v[2:3], 0, s[6:7]
	s_nop 0
	s_waitcnt vmcnt(24)
	v_mov_b32_e32 v12, v230
	v_mov_b32_e32 v13, v231
	v_pk_mul_f32 v[16:17], v[12:13], v[12:13]
	s_nop 0
	v_add_f32_e32 v0, v0, v16
	v_add_f32_e32 v0, v0, v17
	v_add_f32_e32 v4, v4, v0
	v_cvt_f32_i32_e32 v0, v6
	v_pk_add_f32 v[14:15], v[8:9], v[12:13]
	v_pk_add_f32 v[8:9], v[8:9], v[12:13] neg_lo:[0,1] neg_hi:[0,1]
	v_mul_f32_e32 v7, 0x38800000, v0
	v_sin_f32_e32 v18, v7
	v_cos_f32_e32 v16, v7
	v_pk_add_f32 v[12:13], v[8:9], 0 op_sel_hi:[1,0]
	v_pk_add_f32 v[20:21], v[8:9], 0 op_sel_hi:[1,0] neg_lo:[1,0] neg_hi:[1,0]
	v_xor_b32_e32 v17, 0x80000000, v18
	v_mov_b32_e32 v23, v21
	v_pk_mov_b32 v[20:21], v[20:21], v[12:13] op_sel:[1,0]
	v_mov_b32_e32 v22, v12
	v_pk_mul_f32 v[20:21], v[18:19], v[20:21] op_sel_hi:[0,1]
	s_nop 0
	v_pk_fma_f32 v[12:13], v[16:17], v[12:13], v[20:21]
	v_pk_fma_f32 v[20:21], v[16:17], v[22:23], v[20:21] op_sel_hi:[0,1,1] neg_lo:[0,0,1] neg_hi:[0,0,1]
	v_add_f32_e32 v0, v14, v15
	v_mov_b32_e32 v13, v21
	ds_write2st64_b64 v5, v[0:1], v[12:13] offset1:64
	v_mov_b32_e32 v19, v16
	v_mov_b32_e32 v12, v18
	v_mov_b32_e32 v13, v17
	v_pk_mul_f32 v[12:13], v[18:19], v[12:13]
	v_pk_add_f32 v[14:15], v[14:15], v[14:15] op_sel:[0,1] op_sel_hi:[0,1] neg_lo:[0,1] neg_hi:[0,1]
	v_pk_fma_f32 v[20:21], v[16:17], v[16:17], v[12:13] op_sel_hi:[0,1,1] neg_lo:[0,0,1] neg_hi:[0,0,1]
	v_pk_fma_f32 v[12:13], v[16:17], v[16:17], v[12:13] op_sel_hi:[0,1,1]
	s_nop 0
	v_mov_b32_e32 v23, v13
	v_pk_mov_b32 v[12:13], v[12:13], v[20:21] op_sel:[1,0]
	v_mov_b32_e32 v22, v20
	v_pk_mul_f32 v[12:13], v[12:13], 0 op_sel_hi:[1,0]
	v_add_f32_e32 v24, 0, v9
	v_pk_fma_f32 v[20:21], v[20:21], v[14:15], v[12:13] neg_lo:[0,0,1] neg_hi:[0,0,1]
	v_pk_fma_f32 v[12:13], v[22:23], v[14:15], v[12:13]
	v_add_u32_e32 v0, 0x10000, v5
	v_mov_b32_e32 v21, v13
	v_pk_mul_f32 v[12:13], v[18:19], v[22:23] op_sel_hi:[0,1]
	s_nop 0
	v_pk_fma_f32 v[14:15], v[16:17], v[22:23], v[12:13] op_sel:[0,0,1] op_sel_hi:[0,1,0]
	v_pk_fma_f32 v[12:13], v[16:17], v[22:23], v[12:13] op_sel:[0,0,1] op_sel_hi:[0,1,0] neg_lo:[0,0,1] neg_hi:[0,0,1]
	s_nop 0
	v_mov_b32_e32 v17, v13
	v_pk_mov_b32 v[12:13], v[12:13], v[14:15] op_sel:[1,0]
	v_mov_b32_e32 v16, v14
	v_pk_mul_f32 v[12:13], v[24:25], v[12:13] op_sel_hi:[0,1]
	s_nop 0
	v_pk_fma_f32 v[14:15], v[8:9], v[14:15], v[12:13] neg_lo:[0,0,1] neg_hi:[0,0,1]
	v_pk_fma_f32 v[8:9], v[8:9], v[16:17], v[12:13] op_sel_hi:[0,1,1]
	ds_write_b64 v0, v[20:21]
	v_add_u32_e32 v0, 0x18000, v5
	v_mov_b32_e32 v15, v9
	ds_write_b64 v0, v[14:15]
	v_add_u32_e32 v0, 0x200, v6
	v_add_u32_e32 v5, 0x1000, v5
	v_mov_b32_e32 v6, v0
	s_nop 0
	v_add_co_u32_e32 v8, vcc, 0xffff4000, v2
	s_nop 1
	v_addc_co_u32_e32 v9, vcc, -1, v3, vcc
	v_add_co_u32_e32 v12, vcc, 0xffff8000, v2
	s_nop 0
	v_addc_co_u32_e32 v13, vcc, -1, v3, vcc
	s_nop 0
	v_add_co_u32_e32 v12, vcc, 0xffffc000, v2
	s_waitcnt vmcnt(22)
	v_mov_b32_e32 v8, v232
	v_mov_b32_e32 v9, v233
	v_pk_mul_f32 v[14:15], v[8:9], v[8:9]
	v_addc_co_u32_e32 v13, vcc, -1, v3, vcc
	s_nop 0
	v_add_f32_e32 v0, v14, v15
	s_nop 0
	v_lshl_add_u64 v[2:3], v[2:3], 0, s[6:7]
	s_nop 0
	s_waitcnt vmcnt(20)
; DI float2 twid(float r) { return float2{__builtin_amdgcn_cosf(r), -__builtin_amdgcn_sinf(r)}; }
; DI void bfly_fwd(float2 a0, float2 a1, float2 a2, float2 a3, float r, float2& o0, float2& o1, float2& o2, float2& o3) {
;   float2 t0 = {a0.x + a2.x, a0.y + a2.y}, t1 = {a0.x - a2.x, a0.y - a2.y}, t2 = {a1.x + a3.x, a1.y + a3.y}, t3 = {a1.x - a3.x, a1.y - a3.y};
;   float2 b0 = {t0.x + t2.x, t0.y + t2.y}, b2 = {t0.x - t2.x, t0.y - t2.y}, b1 = {t1.x + t3.y, t1.y - t3.x}, b3 = {t1.x - t3.y, t1.y + t3.x};
;   float2 w1 = twid(r), w2 = cmul(w1, w1), w3 = cmul(w2, w1);
;   o0 = b0; o1 = cmul(b1, w1); o2 = cmul(b2, w2); o3 = cmul(b3, w3);
; }
; template <int LOGN> DI void filtfft_item(const Params& p, int ch, int cc, const float* kr, float2* kh) {
;     ...
;     constexpr int Q = N / 4;
;     for (int i = tid; i < Q; i += NTHR) { float k0 = kr[i], k1 = kr[i + Q], k2 = kr[i + 2 * Q], k3 = kr[i + 3 * Q]; ss += k0 * k0 + k1 * k1 + k2 * k2 + k3 * k3; float2 o0, o1, o2, o3;
;       bfly_fwd(float2{k0, 0.f}, float2{k1, 0.f}, float2{k2, 0.f}, float2{k3, 0.f}, (float)i * (1.f / N), o0, o1, o2, o3);
;       z[i] = o0; z[i + Q] = o1; z[i + 2 * Q] = o2; z[i + 3 * Q] = o3; }
	v_mov_b32_e32 v12, v234
	v_mov_b32_e32 v13, v235
	v_pk_mul_f32 v[16:17], v[12:13], v[12:13]
	s_nop 0
	v_add_f32_e32 v0, v0, v16
	v_add_f32_e32 v0, v0, v17
	v_add_f32_e32 v4, v4, v0
	v_cvt_f32_i32_e32 v0, v6
	v_pk_add_f32 v[14:15], v[8:9], v[12:13]
	v_pk_add_f32 v[8:9], v[8:9], v[12:13] neg_lo:[0,1] neg_hi:[0,1]
	v_mul_f32_e32 v7, 0x38800000, v0
	v_sin_f32_e32 v18, v7
	v_cos_f32_e32 v16, v7
	v_pk_add_f32 v[12:13], v[8:9], 0 op_sel_hi:[1,0]
	v_pk_add_f32 v[20:21], v[8:9], 0 op_sel_hi:[1,0] neg_lo:[1,0] neg_hi:[1,0]
	v_xor_b32_e32 v17, 0x80000000, v18
	v_mov_b32_e32 v23, v21
	v_pk_mov_b32 v[20:21], v[20:21], v[12:13] op_sel:[1,0]
	v_mov_b32_e32 v22, v12
	v_pk_mul_f32 v[20:21], v[18:19], v[20:21] op_sel_hi:[0,1]
	s_nop 0
	v_pk_fma_f32 v[12:13], v[16:17], v[12:13], v[20:21]
	v_pk_fma_f32 v[20:21], v[16:17], v[22:23], v[20:21] op_sel_hi:[0,1,1] neg_lo:[0,0,1] neg_hi:[0,0,1]
	v_add_f32_e32 v0, v14, v15
	v_mov_b32_e32 v13, v21
	ds_write2st64_b64 v5, v[0:1], v[12:13] offset1:64
	v_mov_b32_e32 v19, v16
	v_mov_b32_e32 v12, v18
	v_mov_b32_e32 v13, v17
	v_pk_mul_f32 v[12:13], v[18:19], v[12:13]
	v_pk_add_f32 v[14:15], v[14:15], v[14:15] op_sel:[0,1] op_sel_hi:[0,1] neg_lo:[0,1] neg_hi:[0,1]
	v_pk_fma_f32 v[20:21], v[16:17], v[16:17], v[12:13] op_sel_hi:[0,1,1] neg_lo:[0,0,1] neg_hi:[0,0,1]
	v_pk_fma_f32 v[12:13], v[16:17], v[16:17], v[12:13] op_sel_hi:[0,1,1]
	s_nop 0
	v_mov_b32_e32 v23, v13
	v_pk_mov_b32 v[12:13], v[12:13], v[20:21] op_sel:[1,0]
	v_mov_b32_e32 v22, v20
	v_pk_mul_f32 v[12:13], v[12:13], 0 op_sel_hi:[1,0]
	v_add_f32_e32 v24, 0, v9
	v_pk_fma_f32 v[20:21], v[20:21], v[14:15], v[12:13] neg_lo:[0,0,1] neg_hi:[0,0,1]
	v_pk_fma_f32 v[12:13], v[22:23], v[14:15], v[12:13]
	v_add_u32_e32 v0, 0x10000, v5
	v_mov_b32_e32 v21, v13
	v_pk_mul_f32 v[12:13], v[18:19], v[22:23] op_sel_hi:[0,1]
	s_nop 0
	v_pk_fma_f32 v[14:15], v[16:17], v[22:23], v[12:13] op_sel:[0,0,1] op_sel_hi:[0,1,0]
	v_pk_fma_f32 v[12:13], v[16:17], v[22:23], v[12:13] op_sel:[0,0,1] op_sel_hi:[0,1,0] neg_lo:[0,0,1] neg_hi:[0,0,1]
	s_nop 0
	v_mov_b32_e32 v17, v13
	v_pk_mov_b32 v[12:13], v[12:13], v[14:15] op_sel:[1,0]
	v_mov_b32_e32 v16, v14
	v_pk_mul_f32 v[12:13], v[24:25], v[12:13] op_sel_hi:[0,1]
	s_nop 0
	v_pk_fma_f32 v[14:15], v[8:9], v[14:15], v[12:13] neg_lo:[0,0,1] neg_hi:[0,0,1]
	v_pk_fma_f32 v[8:9], v[8:9], v[16:17], v[12:13] op_sel_hi:[0,1,1]
	ds_write_b64 v0, v[20:21]
	v_add_u32_e32 v0, 0x18000, v5
	v_mov_b32_e32 v15, v9
	ds_write_b64 v0, v[14:15]
	v_add_u32_e32 v0, 0x200, v6
	v_add_u32_e32 v5, 0x1000, v5
	v_mov_b32_e32 v6, v0
	s_nop 0
	v_add_co_u32_e32 v8, vcc, 0xffff4000, v2
	s_nop 1
	v_addc_co_u32_e32 v9, vcc, -1, v3, vcc
	v_add_co_u32_e32 v12, vcc, 0xffff8000, v2
	s_nop 0
	v_addc_co_u32_e32 v13, vcc, -1, v3, vcc
	s_nop 0
	v_add_co_u32_e32 v12, vcc, 0xffffc000, v2
	s_waitcnt vmcnt(18)
	v_mov_b32_e32 v8, v236
	v_mov_b32_e32 v9, v237
	v_pk_mul_f32 v[14:15], v[8:9], v[8:9]
	v_addc_co_u32_e32 v13, vcc, -1, v3, vcc
	s_nop 0
	v_add_f32_e32 v0, v14, v15
	s_nop 0
	v_lshl_add_u64 v[2:3], v[2:3], 0, s[6:7]
	s_nop 0
	s_waitcnt vmcnt(16)
	v_mov_b32_e32 v12, v238
	v_mov_b32_e32 v13, v239
	v_pk_mul_f32 v[16:17], v[12:13], v[12:13]
	s_nop 0
	v_add_f32_e32 v0, v0, v16
	v_add_f32_e32 v0, v0, v17
	v_add_f32_e32 v4, v4, v0
	v_cvt_f32_i32_e32 v0, v6
	v_pk_add_f32 v[14:15], v[8:9], v[12:13]
	v_pk_add_f32 v[8:9], v[8:9], v[12:13] neg_lo:[0,1] neg_hi:[0,1]
	v_mul_f32_e32 v7, 0x38800000, v0
	v_sin_f32_e32 v18, v7
	v_cos_f32_e32 v16, v7
	v_pk_add_f32 v[12:13], v[8:9], 0 op_sel_hi:[1,0]
	v_pk_add_f32 v[20:21], v[8:9], 0 op_sel_hi:[1,0] neg_lo:[1,0] neg_hi:[1,0]
	v_xor_b32_e32 v17, 0x80000000, v18
	v_mov_b32_e32 v23, v21
	v_pk_mov_b32 v[20:21], v[20:21], v[12:13] op_sel:[1,0]
	v_mov_b32_e32 v22, v12
	v_pk_mul_f32 v[20:21], v[18:19], v[20:21] op_sel_hi:[0,1]
	s_nop 0
	v_pk_fma_f32 v[12:13], v[16:17], v[12:13], v[20:21]
	v_pk_fma_f32 v[20:21], v[16:17], v[22:23], v[20:21] op_sel_hi:[0,1,1] neg_lo:[0,0,1] neg_hi:[0,0,1]
	v_add_f32_e32 v0, v14, v15
	v_mov_b32_e32 v13, v21
	ds_write2st64_b64 v5, v[0:1], v[12:13] offset1:64
	v_mov_b32_e32 v19, v16
	v_mov_b32_e32 v12, v18
	v_mov_b32_e32 v13, v17
	v_pk_mul_f32 v[12:13], v[18:19], v[12:13]
	v_pk_add_f32 v[14:15], v[14:15], v[14:15] op_sel:[0,1] op_sel_hi:[0,1] neg_lo:[0,1] neg_hi:[0,1]
	v_pk_fma_f32 v[20:21], v[16:17], v[16:17], v[12:13] op_sel_hi:[0,1,1] neg_lo:[0,0,1] neg_hi:[0,0,1]
	v_pk_fma_f32 v[12:13], v[16:17], v[16:17], v[12:13] op_sel_hi:[0,1,1]
	s_nop 0
	v_mov_b32_e32 v23, v13
	v_pk_mov_b32 v[12:13], v[12:13], v[20:21] op_sel:[1,0]
	v_mov_b32_e32 v22, v20
	v_pk_mul_f32 v[12:13], v[12:13], 0 op_sel_hi:[1,0]
	v_add_f32_e32 v24, 0, v9
	v_pk_fma_f32 v[20:21], v[20:21], v[14:15], v[12:13] neg_lo:[0,0,1] neg_hi:[0,0,1]
	v_pk_fma_f32 v[12:13], v[22:23], v[14:15], v[12:13]
	v_add_u32_e32 v0, 0x10000, v5
	v_mov_b32_e32 v21, v13
	v_pk_mul_f32 v[12:13], v[18:19], v[22:23] op_sel_hi:[0,1]
	s_nop 0
	v_pk_fma_f32 v[14:15], v[16:17], v[22:23], v[12:13] op_sel:[0,0,1] op_sel_hi:[0,1,0]
	v_pk_fma_f32 v[12:13], v[16:17], v[22:23], v[12:13] op_sel:[0,0,1] op_sel_hi:[0,1,0] neg_lo:[0,0,1] neg_hi:[0,0,1]
	s_nop 0
	v_mov_b32_e32 v17, v13
	v_pk_mov_b32 v[12:13], v[12:13], v[14:15] op_sel:[1,0]
	v_mov_b32_e32 v16, v14
	v_pk_mul_f32 v[12:13], v[24:25], v[12:13] op_sel_hi:[0,1]
	s_nop 0
	v_pk_fma_f32 v[14:15], v[8:9], v[14:15], v[12:13] neg_lo:[0,0,1] neg_hi:[0,0,1]
	v_pk_fma_f32 v[8:9], v[8:9], v[16:17], v[12:13] op_sel_hi:[0,1,1]
	ds_write_b64 v0, v[20:21]
	v_add_u32_e32 v0, 0x18000, v5
	v_mov_b32_e32 v15, v9
	ds_write_b64 v0, v[14:15]
	v_add_u32_e32 v0, 0x200, v6
	v_add_u32_e32 v5, 0x1000, v5
	v_mov_b32_e32 v6, v0
	s_nop 0
	v_add_co_u32_e32 v8, vcc, 0xffff4000, v2
	s_nop 1
	v_addc_co_u32_e32 v9, vcc, -1, v3, vcc
	v_add_co_u32_e32 v12, vcc, 0xffff8000, v2
	s_nop 0
	v_addc_co_u32_e32 v13, vcc, -1, v3, vcc
	s_nop 0
	v_add_co_u32_e32 v12, vcc, 0xffffc000, v2
	s_waitcnt vmcnt(14)
; DI float2 twid(float r) { return float2{__builtin_amdgcn_cosf(r), -__builtin_amdgcn_sinf(r)}; }
; DI void bfly_fwd(float2 a0, float2 a1, float2 a2, float2 a3, float r, float2& o0, float2& o1, float2& o2, float2& o3) {
;   float2 t0 = {a0.x + a2.x, a0.y + a2.y}, t1 = {a0.x - a2.x, a0.y - a2.y}, t2 = {a1.x + a3.x, a1.y + a3.y}, t3 = {a1.x - a3.x, a1.y - a3.y};
;   float2 b0 = {t0.x + t2.x, t0.y + t2.y}, b2 = {t0.x - t2.x, t0.y - t2.y}, b1 = {t1.x + t3.y, t1.y - t3.x}, b3 = {t1.x - t3.y, t1.y + t3.x};
;   float2 w1 = twid(r), w2 = cmul(w1, w1), w3 = cmul(w2, w1);
;   o0 = b0; o1 = cmul(b1, w1); o2 = cmul(b2, w2); o3 = cmul(b3, w3);
; }
; template <int LOGN> DI void filtfft_item(const Params& p, int ch, int cc, const float* kr, float2* kh) {
;     ...
;     constexpr int Q = N / 4;
;     for (int i = tid; i < Q; i += NTHR) { float k0 = kr[i], k1 = kr[i + Q], k2 = kr[i + 2 * Q], k3 = kr[i + 3 * Q]; ss += k0 * k0 + k1 * k1 + k2 * k2 + k3 * k3; float2 o0, o1, o2, o3;
;       bfly_fwd(float2{k0, 0.f}, float2{k1, 0.f}, float2{k2, 0.f}, float2{k3, 0.f}, (float)i * (1.f / N), o0, o1, o2, o3);
;       z[i] = o0; z[i + Q] = o1; z[i + 2 * Q] = o2; z[i + 3 * Q] = o3; }
	v_mov_b32_e32 v8, v241
	v_mov_b32_e32 v9, v242
	v_pk_mul_f32 v[14:15], v[8:9], v[8:9]
	v_addc_co_u32_e32 v13, vcc, -1, v3, vcc
	s_nop 0
	v_add_f32_e32 v0, v14, v15
	s_nop 0
	v_lshl_add_u64 v[2:3], v[2:3], 0, s[6:7]
	s_nop 0
	s_waitcnt vmcnt(12)
	v_mov_b32_e32 v12, v243
	v_mov_b32_e32 v13, v244
	v_pk_mul_f32 v[16:17], v[12:13], v[12:13]
	s_nop 0
	v_add_f32_e32 v0, v0, v16
	v_add_f32_e32 v0, v0, v17
	v_add_f32_e32 v4, v4, v0
	v_cvt_f32_i32_e32 v0, v6
	v_pk_add_f32 v[14:15], v[8:9], v[12:13]
	v_pk_add_f32 v[8:9], v[8:9], v[12:13] neg_lo:[0,1] neg_hi:[0,1]
	v_mul_f32_e32 v7, 0x38800000, v0
	v_sin_f32_e32 v18, v7
	v_cos_f32_e32 v16, v7
	v_pk_add_f32 v[12:13], v[8:9], 0 op_sel_hi:[1,0]
	v_pk_add_f32 v[20:21], v[8:9], 0 op_sel_hi:[1,0] neg_lo:[1,0] neg_hi:[1,0]
	v_xor_b32_e32 v17, 0x80000000, v18
	v_mov_b32_e32 v23, v21
	v_pk_mov_b32 v[20:21], v[20:21], v[12:13] op_sel:[1,0]
	v_mov_b32_e32 v22, v12
	v_pk_mul_f32 v[20:21], v[18:19], v[20:21] op_sel_hi:[0,1]
	s_nop 0
	v_pk_fma_f32 v[12:13], v[16:17], v[12:13], v[20:21]
	v_pk_fma_f32 v[20:21], v[16:17], v[22:23], v[20:21] op_sel_hi:[0,1,1] neg_lo:[0,0,1] neg_hi:[0,0,1]
	v_add_f32_e32 v0, v14, v15
	v_mov_b32_e32 v13, v21
	ds_write2st64_b64 v5, v[0:1], v[12:13] offset1:64
	v_mov_b32_e32 v19, v16
	v_mov_b32_e32 v12, v18
	v_mov_b32_e32 v13, v17
	v_pk_mul_f32 v[12:13], v[18:19], v[12:13]
	v_pk_add_f32 v[14:15], v[14:15], v[14:15] op_sel:[0,1] op_sel_hi:[0,1] neg_lo:[0,1] neg_hi:[0,1]
	v_pk_fma_f32 v[20:21], v[16:17], v[16:17], v[12:13] op_sel_hi:[0,1,1] neg_lo:[0,0,1] neg_hi:[0,0,1]
	v_pk_fma_f32 v[12:13], v[16:17], v[16:17], v[12:13] op_sel_hi:[0,1,1]
	s_nop 0
	v_mov_b32_e32 v23, v13
	v_pk_mov_b32 v[12:13], v[12:13], v[20:21] op_sel:[1,0]
	v_mov_b32_e32 v22, v20
	v_pk_mul_f32 v[12:13], v[12:13], 0 op_sel_hi:[1,0]
	v_add_f32_e32 v24, 0, v9
	v_pk_fma_f32 v[20:21], v[20:21], v[14:15], v[12:13] neg_lo:[0,0,1] neg_hi:[0,0,1]
	v_pk_fma_f32 v[12:13], v[22:23], v[14:15], v[12:13]
	v_add_u32_e32 v0, 0x10000, v5
	v_mov_b32_e32 v21, v13
	v_pk_mul_f32 v[12:13], v[18:19], v[22:23] op_sel_hi:[0,1]
	s_nop 0
	v_pk_fma_f32 v[14:15], v[16:17], v[22:23], v[12:13] op_sel:[0,0,1] op_sel_hi:[0,1,0]
	v_pk_fma_f32 v[12:13], v[16:17], v[22:23], v[12:13] op_sel:[0,0,1] op_sel_hi:[0,1,0] neg_lo:[0,0,1] neg_hi:[0,0,1]
	s_nop 0
	v_mov_b32_e32 v17, v13
	v_pk_mov_b32 v[12:13], v[12:13], v[14:15] op_sel:[1,0]
	v_mov_b32_e32 v16, v14
	v_pk_mul_f32 v[12:13], v[24:25], v[12:13] op_sel_hi:[0,1]
	s_nop 0
	v_pk_fma_f32 v[14:15], v[8:9], v[14:15], v[12:13] neg_lo:[0,0,1] neg_hi:[0,0,1]
	v_pk_fma_f32 v[8:9], v[8:9], v[16:17], v[12:13] op_sel_hi:[0,1,1]
	ds_write_b64 v0, v[20:21]
	v_add_u32_e32 v0, 0x18000, v5
	v_mov_b32_e32 v15, v9
	ds_write_b64 v0, v[14:15]
	v_add_u32_e32 v0, 0x200, v6
	v_add_u32_e32 v5, 0x1000, v5
	v_mov_b32_e32 v6, v0
	s_nop 0
	v_add_co_u32_e32 v8, vcc, 0xffff4000, v2
	s_nop 1
	v_addc_co_u32_e32 v9, vcc, -1, v3, vcc
	v_add_co_u32_e32 v12, vcc, 0xffff8000, v2
	s_nop 0
	v_addc_co_u32_e32 v13, vcc, -1, v3, vcc
	s_nop 0
	v_add_co_u32_e32 v12, vcc, 0xffffc000, v2
	s_waitcnt vmcnt(10)
	v_mov_b32_e32 v8, v245
	v_mov_b32_e32 v9, v246
	v_pk_mul_f32 v[14:15], v[8:9], v[8:9]
	v_addc_co_u32_e32 v13, vcc, -1, v3, vcc
	s_nop 0
	v_add_f32_e32 v0, v14, v15
	s_nop 0
	v_lshl_add_u64 v[2:3], v[2:3], 0, s[6:7]
	s_nop 0
	s_waitcnt vmcnt(8)
	v_mov_b32_e32 v12, v247
	v_mov_b32_e32 v13, v248
	v_pk_mul_f32 v[16:17], v[12:13], v[12:13]
	s_nop 0
	v_add_f32_e32 v0, v0, v16
	v_add_f32_e32 v0, v0, v17
	v_add_f32_e32 v4, v4, v0
	v_cvt_f32_i32_e32 v0, v6
	v_pk_add_f32 v[14:15], v[8:9], v[12:13]
	v_pk_add_f32 v[8:9], v[8:9], v[12:13] neg_lo:[0,1] neg_hi:[0,1]
	v_mul_f32_e32 v7, 0x38800000, v0
	v_sin_f32_e32 v18, v7
	v_cos_f32_e32 v16, v7
	v_pk_add_f32 v[12:13], v[8:9], 0 op_sel_hi:[1,0]
	v_pk_add_f32 v[20:21], v[8:9], 0 op_sel_hi:[1,0] neg_lo:[1,0] neg_hi:[1,0]
	v_xor_b32_e32 v17, 0x80000000, v18
	v_mov_b32_e32 v23, v21
	v_pk_mov_b32 v[20:21], v[20:21], v[12:13] op_sel:[1,0]
	v_mov_b32_e32 v22, v12
	v_pk_mul_f32 v[20:21], v[18:19], v[20:21] op_sel_hi:[0,1]
	s_nop 0
	v_pk_fma_f32 v[12:13], v[16:17], v[12:13], v[20:21]
	v_pk_fma_f32 v[20:21], v[16:17], v[22:23], v[20:21] op_sel_hi:[0,1,1] neg_lo:[0,0,1] neg_hi:[0,0,1]
	v_add_f32_e32 v0, v14, v15
	v_mov_b32_e32 v13, v21
	ds_write2st64_b64 v5, v[0:1], v[12:13] offset1:64
	v_mov_b32_e32 v19, v16
	v_mov_b32_e32 v12, v18
	v_mov_b32_e32 v13, v17
	v_pk_mul_f32 v[12:13], v[18:19], v[12:13]
	v_pk_add_f32 v[14:15], v[14:15], v[14:15] op_sel:[0,1] op_sel_hi:[0,1] neg_lo:[0,1] neg_hi:[0,1]
	v_pk_fma_f32 v[20:21], v[16:17], v[16:17], v[12:13] op_sel_hi:[0,1,1] neg_lo:[0,0,1] neg_hi:[0,0,1]
	v_pk_fma_f32 v[12:13], v[16:17], v[16:17], v[12:13] op_sel_hi:[0,1,1]
	s_nop 0
	v_mov_b32_e32 v23, v13
	v_pk_mov_b32 v[12:13], v[12:13], v[20:21] op_sel:[1,0]
	v_mov_b32_e32 v22, v20
	v_pk_mul_f32 v[12:13], v[12:13], 0 op_sel_hi:[1,0]
	v_add_f32_e32 v24, 0, v9
	v_pk_fma_f32 v[20:21], v[20:21], v[14:15], v[12:13] neg_lo:[0,0,1] neg_hi:[0,0,1]
	v_pk_fma_f32 v[12:13], v[22:23], v[14:15], v[12:13]
	v_add_u32_e32 v0, 0x10000, v5
	v_mov_b32_e32 v21, v13
	v_pk_mul_f32 v[12:13], v[18:19], v[22:23] op_sel_hi:[0,1]
	s_nop 0
	v_pk_fma_f32 v[14:15], v[16:17], v[22:23], v[12:13] op_sel:[0,0,1] op_sel_hi:[0,1,0]
	v_pk_fma_f32 v[12:13], v[16:17], v[22:23], v[12:13] op_sel:[0,0,1] op_sel_hi:[0,1,0] neg_lo:[0,0,1] neg_hi:[0,0,1]
	s_nop 0
	v_mov_b32_e32 v17, v13
	v_pk_mov_b32 v[12:13], v[12:13], v[14:15] op_sel:[1,0]
	v_mov_b32_e32 v16, v14
	v_pk_mul_f32 v[12:13], v[24:25], v[12:13] op_sel_hi:[0,1]
	s_nop 0
	v_pk_fma_f32 v[14:15], v[8:9], v[14:15], v[12:13] neg_lo:[0,0,1] neg_hi:[0,0,1]
	v_pk_fma_f32 v[8:9], v[8:9], v[16:17], v[12:13] op_sel_hi:[0,1,1]
	ds_write_b64 v0, v[20:21]
	v_add_u32_e32 v0, 0x18000, v5
	v_mov_b32_e32 v15, v9
	ds_write_b64 v0, v[14:15]
	v_add_u32_e32 v0, 0x200, v6
	v_add_u32_e32 v5, 0x1000, v5
	v_mov_b32_e32 v6, v0
	s_nop 0
	v_add_co_u32_e32 v8, vcc, 0xffff4000, v2
	s_nop 1
	v_addc_co_u32_e32 v9, vcc, -1, v3, vcc
	v_add_co_u32_e32 v12, vcc, 0xffff8000, v2
	s_nop 0
	v_addc_co_u32_e32 v13, vcc, -1, v3, vcc
	s_nop 0
	v_add_co_u32_e32 v12, vcc, 0xffffc000, v2
	s_waitcnt vmcnt(6)
; DI float2 twid(float r) { return float2{__builtin_amdgcn_cosf(r), -__builtin_amdgcn_sinf(r)}; }
; DI void bfly_fwd(float2 a0, float2 a1, float2 a2, float2 a3, float r, float2& o0, float2& o1, float2& o2, float2& o3) {
;   float2 t0 = {a0.x + a2.x, a0.y + a2.y}, t1 = {a0.x - a2.x, a0.y - a2.y}, t2 = {a1.x + a3.x, a1.y + a3.y}, t3 = {a1.x - a3.x, a1.y - a3.y};
;   float2 b0 = {t0.x + t2.x, t0.y + t2.y}, b2 = {t0.x - t2.x, t0.y - t2.y}, b1 = {t1.x + t3.y, t1.y - t3.x}, b3 = {t1.x - t3.y, t1.y + t3.x};
;   float2 w1 = twid(r), w2 = cmul(w1, w1), w3 = cmul(w2, w1);
;   o0 = b0; o1 = cmul(b1, w1); o2 = cmul(b2, w2); o3 = cmul(b3, w3);
; }
; template <int LOGN> DI void filtfft_item(const Params& p, int ch, int cc, const float* kr, float2* kh) {
;     ...
;     constexpr int Q = N / 4;
;     for (int i = tid; i < Q; i += NTHR) { float k0 = kr[i], k1 = kr[i + Q], k2 = kr[i + 2 * Q], k3 = kr[i + 3 * Q]; ss += k0 * k0 + k1 * k1 + k2 * k2 + k3 * k3; float2 o0, o1, o2, o3;
;       bfly_fwd(float2{k0, 0.f}, float2{k1, 0.f}, float2{k2, 0.f}, float2{k3, 0.f}, (float)i * (1.f / N), o0, o1, o2, o3);
;       z[i] = o0; z[i + Q] = o1; z[i + 2 * Q] = o2; z[i + 3 * Q] = o3; }
	v_mov_b32_e32 v8, v249
	v_mov_b32_e32 v9, v250
	v_pk_mul_f32 v[14:15], v[8:9], v[8:9]
	v_addc_co_u32_e32 v13, vcc, -1, v3, vcc
	s_nop 0
	v_add_f32_e32 v0, v14, v15
	s_nop 0
	v_lshl_add_u64 v[2:3], v[2:3], 0, s[6:7]
	s_nop 0
	s_waitcnt vmcnt(4)
	v_mov_b32_e32 v12, v251
	v_mov_b32_e32 v13, v252
	v_pk_mul_f32 v[16:17], v[12:13], v[12:13]
	s_nop 0
	v_add_f32_e32 v0, v0, v16
	v_add_f32_e32 v0, v0, v17
	v_add_f32_e32 v4, v4, v0
	v_cvt_f32_i32_e32 v0, v6
	v_pk_add_f32 v[14:15], v[8:9], v[12:13]
	v_pk_add_f32 v[8:9], v[8:9], v[12:13] neg_lo:[0,1] neg_hi:[0,1]
	v_mul_f32_e32 v7, 0x38800000, v0
	v_sin_f32_e32 v18, v7
	v_cos_f32_e32 v16, v7
	v_pk_add_f32 v[12:13], v[8:9], 0 op_sel_hi:[1,0]
	v_pk_add_f32 v[20:21], v[8:9], 0 op_sel_hi:[1,0] neg_lo:[1,0] neg_hi:[1,0]
	v_xor_b32_e32 v17, 0x80000000, v18
	v_mov_b32_e32 v23, v21
	v_pk_mov_b32 v[20:21], v[20:21], v[12:13] op_sel:[1,0]
	v_mov_b32_e32 v22, v12
	v_pk_mul_f32 v[20:21], v[18:19], v[20:21] op_sel_hi:[0,1]
	s_nop 0
	v_pk_fma_f32 v[12:13], v[16:17], v[12:13], v[20:21]
	v_pk_fma_f32 v[20:21], v[16:17], v[22:23], v[20:21] op_sel_hi:[0,1,1] neg_lo:[0,0,1] neg_hi:[0,0,1]
	v_add_f32_e32 v0, v14, v15
	v_mov_b32_e32 v13, v21
	ds_write2st64_b64 v5, v[0:1], v[12:13] offset1:64
	v_mov_b32_e32 v19, v16
	v_mov_b32_e32 v12, v18
	v_mov_b32_e32 v13, v17
	v_pk_mul_f32 v[12:13], v[18:19], v[12:13]
	v_pk_add_f32 v[14:15], v[14:15], v[14:15] op_sel:[0,1] op_sel_hi:[0,1] neg_lo:[0,1] neg_hi:[0,1]
	v_pk_fma_f32 v[20:21], v[16:17], v[16:17], v[12:13] op_sel_hi:[0,1,1] neg_lo:[0,0,1] neg_hi:[0,0,1]
	v_pk_fma_f32 v[12:13], v[16:17], v[16:17], v[12:13] op_sel_hi:[0,1,1]
	s_nop 0
	v_mov_b32_e32 v23, v13
	v_pk_mov_b32 v[12:13], v[12:13], v[20:21] op_sel:[1,0]
	v_mov_b32_e32 v22, v20
	v_pk_mul_f32 v[12:13], v[12:13], 0 op_sel_hi:[1,0]
	v_add_f32_e32 v24, 0, v9
	v_pk_fma_f32 v[20:21], v[20:21], v[14:15], v[12:13] neg_lo:[0,0,1] neg_hi:[0,0,1]
	v_pk_fma_f32 v[12:13], v[22:23], v[14:15], v[12:13]
	v_add_u32_e32 v0, 0x10000, v5
	v_mov_b32_e32 v21, v13
	v_pk_mul_f32 v[12:13], v[18:19], v[22:23] op_sel_hi:[0,1]
	s_nop 0
	v_pk_fma_f32 v[14:15], v[16:17], v[22:23], v[12:13] op_sel:[0,0,1] op_sel_hi:[0,1,0]
	v_pk_fma_f32 v[12:13], v[16:17], v[22:23], v[12:13] op_sel:[0,0,1] op_sel_hi:[0,1,0] neg_lo:[0,0,1] neg_hi:[0,0,1]
	s_nop 0
	v_mov_b32_e32 v17, v13
	v_pk_mov_b32 v[12:13], v[12:13], v[14:15] op_sel:[1,0]
	v_mov_b32_e32 v16, v14
	v_pk_mul_f32 v[12:13], v[24:25], v[12:13] op_sel_hi:[0,1]
	s_nop 0
	v_pk_fma_f32 v[14:15], v[8:9], v[14:15], v[12:13] neg_lo:[0,0,1] neg_hi:[0,0,1]
	v_pk_fma_f32 v[8:9], v[8:9], v[16:17], v[12:13] op_sel_hi:[0,1,1]
	ds_write_b64 v0, v[20:21]
	v_add_u32_e32 v0, 0x18000, v5
	v_mov_b32_e32 v15, v9
	ds_write_b64 v0, v[14:15]
	v_add_u32_e32 v0, 0x200, v6
	v_add_u32_e32 v5, 0x1000, v5
	v_mov_b32_e32 v6, v0
	s_nop 0
	v_add_co_u32_e32 v8, vcc, 0xffff4000, v2
	s_nop 1
	v_addc_co_u32_e32 v9, vcc, -1, v3, vcc
	v_add_co_u32_e32 v12, vcc, 0xffff8000, v2
	s_nop 0
	v_addc_co_u32_e32 v13, vcc, -1, v3, vcc
	s_nop 0
	v_add_co_u32_e32 v12, vcc, 0xffffc000, v2
	s_waitcnt vmcnt(2)
	v_mov_b32_e32 v8, v224
	v_mov_b32_e32 v9, v225
	v_pk_mul_f32 v[14:15], v[8:9], v[8:9]
	v_addc_co_u32_e32 v13, vcc, -1, v3, vcc
	s_nop 0
	v_add_f32_e32 v0, v14, v15
	s_nop 0
	v_lshl_add_u64 v[2:3], v[2:3], 0, s[6:7]
	s_nop 0
	s_waitcnt vmcnt(0)
	v_mov_b32_e32 v12, v226
	v_mov_b32_e32 v13, v227
	v_pk_mul_f32 v[16:17], v[12:13], v[12:13]
	s_nop 0
	v_add_f32_e32 v0, v0, v16
	v_add_f32_e32 v0, v0, v17
	v_add_f32_e32 v4, v4, v0
	v_cvt_f32_i32_e32 v0, v6
	v_pk_add_f32 v[14:15], v[8:9], v[12:13]
	v_pk_add_f32 v[8:9], v[8:9], v[12:13] neg_lo:[0,1] neg_hi:[0,1]
	v_mul_f32_e32 v7, 0x38800000, v0
	v_sin_f32_e32 v18, v7
	v_cos_f32_e32 v16, v7
	v_pk_add_f32 v[12:13], v[8:9], 0 op_sel_hi:[1,0]
	v_pk_add_f32 v[20:21], v[8:9], 0 op_sel_hi:[1,0] neg_lo:[1,0] neg_hi:[1,0]
	v_xor_b32_e32 v17, 0x80000000, v18
	v_mov_b32_e32 v23, v21
	v_pk_mov_b32 v[20:21], v[20:21], v[12:13] op_sel:[1,0]
	v_mov_b32_e32 v22, v12
	v_pk_mul_f32 v[20:21], v[18:19], v[20:21] op_sel_hi:[0,1]
	s_nop 0
	v_pk_fma_f32 v[12:13], v[16:17], v[12:13], v[20:21]
	v_pk_fma_f32 v[20:21], v[16:17], v[22:23], v[20:21] op_sel_hi:[0,1,1] neg_lo:[0,0,1] neg_hi:[0,0,1]
	v_add_f32_e32 v0, v14, v15
	v_mov_b32_e32 v13, v21
	ds_write2st64_b64 v5, v[0:1], v[12:13] offset1:64
	v_mov_b32_e32 v19, v16
	v_mov_b32_e32 v12, v18
	v_mov_b32_e32 v13, v17
	v_pk_mul_f32 v[12:13], v[18:19], v[12:13]
	v_pk_add_f32 v[14:15], v[14:15], v[14:15] op_sel:[0,1] op_sel_hi:[0,1] neg_lo:[0,1] neg_hi:[0,1]
	v_pk_fma_f32 v[20:21], v[16:17], v[16:17], v[12:13] op_sel_hi:[0,1,1] neg_lo:[0,0,1] neg_hi:[0,0,1]
	v_pk_fma_f32 v[12:13], v[16:17], v[16:17], v[12:13] op_sel_hi:[0,1,1]
	s_nop 0
	v_mov_b32_e32 v23, v13
	v_pk_mov_b32 v[12:13], v[12:13], v[20:21] op_sel:[1,0]
	v_mov_b32_e32 v22, v20
	v_pk_mul_f32 v[12:13], v[12:13], 0 op_sel_hi:[1,0]
	v_add_f32_e32 v24, 0, v9
	v_pk_fma_f32 v[20:21], v[20:21], v[14:15], v[12:13] neg_lo:[0,0,1] neg_hi:[0,0,1]
	v_pk_fma_f32 v[12:13], v[22:23], v[14:15], v[12:13]
	v_add_u32_e32 v0, 0x10000, v5
	v_mov_b32_e32 v21, v13
	v_pk_mul_f32 v[12:13], v[18:19], v[22:23] op_sel_hi:[0,1]
	s_nop 0
	v_pk_fma_f32 v[14:15], v[16:17], v[22:23], v[12:13] op_sel:[0,0,1] op_sel_hi:[0,1,0]
	v_pk_fma_f32 v[12:13], v[16:17], v[22:23], v[12:13] op_sel:[0,0,1] op_sel_hi:[0,1,0] neg_lo:[0,0,1] neg_hi:[0,0,1]
	s_nop 0
	v_mov_b32_e32 v17, v13
	v_pk_mov_b32 v[12:13], v[12:13], v[14:15] op_sel:[1,0]
	v_mov_b32_e32 v16, v14
	v_pk_mul_f32 v[12:13], v[24:25], v[12:13] op_sel_hi:[0,1]
	s_nop 0
	v_pk_fma_f32 v[14:15], v[8:9], v[14:15], v[12:13] neg_lo:[0,0,1] neg_hi:[0,0,1]
	v_pk_fma_f32 v[8:9], v[8:9], v[16:17], v[12:13] op_sel_hi:[0,1,1]
	ds_write_b64 v0, v[20:21]
	v_add_u32_e32 v0, 0x18000, v5
	v_mov_b32_e32 v15, v9
	ds_write_b64 v0, v[14:15]
	v_add_u32_e32 v0, 0x200, v6
	v_add_u32_e32 v5, 0x1000, v5
	v_mov_b32_e32 v6, v0
	s_nop 0
	s_mov_b64 s[10:11], exec
	s_or_b64 exec, exec, s[10:11]

; DI float2 twid(float r) { return float2{__builtin_amdgcn_cosf(r), -__builtin_amdgcn_sinf(r)}; }
; DI void fftconv2_item(bft* x, const float2* kh) {
;     ...
;   for (int ii = 2 * tid; ii < 2 * L; ii += 2 * NTHR) { const int sel = ii >= L ? 1 : 0, i = ii - sel * L; bft* xa = x + sel * 2 * L; bft* xb = xa + L; float2* z = z0 + sel * N;
;     unsigned wa = *(const unsigned*)(xa + i), wb = *(const unsigned*)(xb + i);
;     float2 x0 = {__uint_as_float(wa << 16), __uint_as_float(wb << 16)}, x1 = {__uint_as_float(wa & 0xffff0000u), __uint_as_float(wb & 0xffff0000u)};
;     z[i] = x0; z[i + 1] = x1; z[L + i] = cmul(x0, twid((float)i * (1.f / N))); z[L + i + 1] = cmul(x1, twid((float)(i + 1) * (1.f / N))); }
.LBB0_1597:
	v_mov_b32_e32 v220, v2
	v_mov_b32_e32 v219, v1
	v_cmp_lt_i32_e32 vcc, s31, v220
	s_nop 1
	v_cndmask_b32_e32 v218, 0, v154, vcc
	v_cndmask_b32_e32 v221, 0, v155, vcc
	v_add_u32_e32 v222, v218, v220
	v_lshlrev_b32_e32 v218, 1, v221
	v_lshl_add_u64 v[224:225], s[14:15], 0, v[218:219]
	v_ashrrev_i32_e32 v223, 31, v222
	v_lshl_add_u64 v[224:225], v[222:223], 1, v[224:225]
	global_load_dword v226, v[224:225], off
	v_add_co_u32_e32 v224, vcc, s24, v224
	s_nop 1
	v_addc_co_u32_e32 v225, vcc, 0, v225, vcc
	global_load_dword v227, v[224:225], off
	v_add_u32_e32 v218, 0x400, v220
	v_mov_b32_e32 v220, v218
	v_cmp_lt_i32_e32 vcc, s31, v220
	s_nop 1
	v_cndmask_b32_e32 v218, 0, v154, vcc
	v_cndmask_b32_e32 v221, 0, v155, vcc
	v_add_u32_e32 v222, v218, v220
	v_lshlrev_b32_e32 v218, 1, v221
	v_lshl_add_u64 v[224:225], s[14:15], 0, v[218:219]
	v_ashrrev_i32_e32 v223, 31, v222
	v_lshl_add_u64 v[224:225], v[222:223], 1, v[224:225]
	global_load_dword v228, v[224:225], off
	v_add_co_u32_e32 v224, vcc, s24, v224
	s_nop 1
	v_addc_co_u32_e32 v225, vcc, 0, v225, vcc
	global_load_dword v229, v[224:225], off
	v_add_u32_e32 v218, 0x400, v220
	v_mov_b32_e32 v220, v218
	v_cmp_lt_i32_e32 vcc, s31, v220
	s_nop 1
	v_cndmask_b32_e32 v218, 0, v154, vcc
	v_cndmask_b32_e32 v221, 0, v155, vcc
	v_add_u32_e32 v222, v218, v220
	v_lshlrev_b32_e32 v218, 1, v221
	v_lshl_add_u64 v[224:225], s[14:15], 0, v[218:219]
	v_ashrrev_i32_e32 v223, 31, v222
	v_lshl_add_u64 v[224:225], v[222:223], 1, v[224:225]
	global_load_dword v230, v[224:225], off
	v_add_co_u32_e32 v224, vcc, s24, v224
	s_nop 1
	v_addc_co_u32_e32 v225, vcc, 0, v225, vcc
	global_load_dword v231, v[224:225], off
	v_add_u32_e32 v218, 0x400, v220
	v_mov_b32_e32 v220, v218
	v_cmp_lt_i32_e32 vcc, s31, v220
	s_nop 1
	v_cndmask_b32_e32 v218, 0, v154, vcc
	v_cndmask_b32_e32 v221, 0, v155, vcc
	v_add_u32_e32 v222, v218, v220
	v_lshlrev_b32_e32 v218, 1, v221
	v_lshl_add_u64 v[224:225], s[14:15], 0, v[218:219]
	v_ashrrev_i32_e32 v223, 31, v222
	v_lshl_add_u64 v[224:225], v[222:223], 1, v[224:225]
	global_load_dword v232, v[224:225], off
	v_add_co_u32_e32 v224, vcc, s24, v224
	s_nop 1
	v_addc_co_u32_e32 v225, vcc, 0, v225, vcc
	global_load_dword v233, v[224:225], off
	v_add_u32_e32 v218, 0x400, v220
	v_mov_b32_e32 v220, v218
	v_cmp_lt_i32_e32 vcc, s31, v220
	s_nop 1
	v_cndmask_b32_e32 v218, 0, v154, vcc
	v_cndmask_b32_e32 v221, 0, v155, vcc
	v_add_u32_e32 v222, v218, v220
	v_lshlrev_b32_e32 v218, 1, v221
	v_lshl_add_u64 v[224:225], s[14:15], 0, v[218:219]
	v_ashrrev_i32_e32 v223, 31, v222
	v_lshl_add_u64 v[224:225], v[222:223], 1, v[224:225]
	global_load_dword v234, v[224:225], off
	v_add_co_u32_e32 v224, vcc, s24, v224
	s_nop 1
	v_addc_co_u32_e32 v225, vcc, 0, v225, vcc
	global_load_dword v235, v[224:225], off
	v_add_u32_e32 v218, 0x400, v220
	v_mov_b32_e32 v220, v218
	v_cmp_lt_i32_e32 vcc, s31, v220
	s_nop 1
	v_cndmask_b32_e32 v218, 0, v154, vcc
	v_cndmask_b32_e32 v221, 0, v155, vcc
	v_add_u32_e32 v222, v218, v220
	v_lshlrev_b32_e32 v218, 1, v221
	v_lshl_add_u64 v[224:225], s[14:15], 0, v[218:219]
	v_ashrrev_i32_e32 v223, 31, v222
	v_lshl_add_u64 v[224:225], v[222:223], 1, v[224:225]
	global_load_dword v236, v[224:225], off
	v_add_co_u32_e32 v224, vcc, s24, v224
	s_nop 1
	v_addc_co_u32_e32 v225, vcc, 0, v225, vcc
	global_load_dword v237, v[224:225], off
	v_add_u32_e32 v218, 0x400, v220
	v_mov_b32_e32 v220, v218
	v_cmp_lt_i32_e32 vcc, s31, v220
	s_nop 1
	v_cndmask_b32_e32 v218, 0, v154, vcc
	v_cndmask_b32_e32 v221, 0, v155, vcc
	v_add_u32_e32 v222, v218, v220
	v_lshlrev_b32_e32 v218, 1, v221
	v_lshl_add_u64 v[224:225], s[14:15], 0, v[218:219]
	v_ashrrev_i32_e32 v223, 31, v222
	v_lshl_add_u64 v[224:225], v[222:223], 1, v[224:225]
	global_load_dword v238, v[224:225], off
	v_add_co_u32_e32 v224, vcc, s24, v224
	s_nop 1
	v_addc_co_u32_e32 v225, vcc, 0, v225, vcc
	global_load_dword v239, v[224:225], off
	v_add_u32_e32 v218, 0x400, v220
	v_mov_b32_e32 v220, v218
	v_cmp_lt_i32_e32 vcc, s31, v220
	s_nop 1
	v_cndmask_b32_e32 v218, 0, v154, vcc
	v_cndmask_b32_e32 v221, 0, v155, vcc
	v_add_u32_e32 v222, v218, v220
	v_lshlrev_b32_e32 v218, 1, v221
	v_lshl_add_u64 v[224:225], s[14:15], 0, v[218:219]
	v_ashrrev_i32_e32 v223, 31, v222
	v_lshl_add_u64 v[224:225], v[222:223], 1, v[224:225]
	global_load_dword v241, v[224:225], off
	v_add_co_u32_e32 v224, vcc, s24, v224
	s_nop 1
	v_addc_co_u32_e32 v225, vcc, 0, v225, vcc
	global_load_dword v242, v[224:225], off
	v_add_u32_e32 v218, 0x400, v220
	v_mov_b32_e32 v220, v218
	v_cmp_lt_i32_e32 vcc, s31, v2
	s_nop 1
	v_cndmask_b32_e32 v0, 0, v154, vcc
	v_cndmask_b32_e32 v3, 0, v155, vcc
	v_add_u32_e32 v4, v0, v2
	v_lshlrev_b32_e32 v0, 1, v3
	v_lshl_add_u64 v[6:7], s[14:15], 0, v[0:1]
	v_ashrrev_i32_e32 v5, 31, v4
	v_lshl_add_u64 v[6:7], v[4:5], 1, v[6:7]
	v_lshlrev_b32_e32 v0, 3, v3
	s_nop 0
	v_add_co_u32_e32 v6, vcc, s24, v6
	v_lshlrev_b32_e32 v5, 3, v4
	s_nop 0
	v_addc_co_u32_e32 v7, vcc, 0, v7, vcc
	s_nop 0
	v_add3_u32 v14, 16, v0, v5
	v_cvt_f32_i32_e32 v0, v4
	v_add_u32_e32 v10, 1, v4
	s_nop 0
	v_mul_f32_e32 v4, 0x39000000, v0
	v_sin_f32_e32 v6, v4
	v_cos_f32_e32 v0, v4
	s_waitcnt vmcnt(15)
	v_mov_b32_e32 v3, v226
	v_lshlrev_b32_e32 v4, 16, v3
	s_waitcnt vmcnt(14)
; DI float2 twid(float r) { return float2{__builtin_amdgcn_cosf(r), -__builtin_amdgcn_sinf(r)}; }
; DI void fftconv2_item(bft* x, const float2* kh) {
;     ...
;   for (int ii = 2 * tid; ii < 2 * L; ii += 2 * NTHR) { const int sel = ii >= L ? 1 : 0, i = ii - sel * L; bft* xa = x + sel * 2 * L; bft* xb = xa + L; float2* z = z0 + sel * N;
;     unsigned wa = *(const unsigned*)(xa + i), wb = *(const unsigned*)(xb + i);
;     float2 x0 = {__uint_as_float(wa << 16), __uint_as_float(wb << 16)}, x1 = {__uint_as_float(wa & 0xffff0000u), __uint_as_float(wb & 0xffff0000u)};
;     z[i] = x0; z[i + 1] = x1; z[L + i] = cmul(x0, twid((float)i * (1.f / N))); z[L + i + 1] = cmul(x1, twid((float)(i + 1) * (1.f / N))); }
	v_mov_b32_e32 v11, v227
	v_lshlrev_b32_e32 v5, 16, v11
	v_pk_mul_f32 v[6:7], v[6:7], v[4:5] op_sel:[0,1] op_sel_hi:[0,0]
	s_nop 0
	v_pk_fma_f32 v[8:9], v[0:1], v[4:5], v[6:7]
	v_pk_fma_f32 v[12:13], v[0:1], v[4:5], v[6:7] op_sel_hi:[0,1,1] neg_lo:[0,0,1] neg_hi:[0,0,1]
	v_cvt_f32_i32_e32 v0, v10
	v_and_b32_e32 v7, 0xffff0000, v11
	v_mov_b32_e32 v9, v13
	v_mul_f32_e32 v6, 0x39000000, v0
	v_sin_f32_e32 v10, v6
	v_cos_f32_e32 v0, v6
	v_and_b32_e32 v6, 0xffff0000, v3
	ds_write_b128 v14, v[4:7]
	v_pk_mul_f32 v[4:5], v[10:11], v[6:7] op_sel:[0,1] op_sel_hi:[0,0]
	s_nop 0
	v_pk_fma_f32 v[10:11], v[0:1], v[6:7], v[4:5]
	v_pk_fma_f32 v[4:5], v[0:1], v[6:7], v[4:5] op_sel_hi:[0,1,1] neg_lo:[0,0,1] neg_hi:[0,0,1]
	v_add_u32_e32 v0, 0x400, v2
	v_mov_b32_e32 v11, v5
	v_mov_b32_e32 v2, v0
	ds_write_b128 v14, v[8:11] offset:32768
	s_nop 0
	v_cmp_lt_i32_e32 vcc, s31, v2
	s_nop 1
	v_cndmask_b32_e32 v0, 0, v154, vcc
	v_cndmask_b32_e32 v3, 0, v155, vcc
	v_add_u32_e32 v4, v0, v2
	v_lshlrev_b32_e32 v0, 1, v3
	v_lshl_add_u64 v[6:7], s[14:15], 0, v[0:1]
	v_ashrrev_i32_e32 v5, 31, v4
	v_lshl_add_u64 v[6:7], v[4:5], 1, v[6:7]
	v_lshlrev_b32_e32 v0, 3, v3
	s_nop 0
	v_add_co_u32_e32 v6, vcc, s24, v6
	v_lshlrev_b32_e32 v5, 3, v4
	s_nop 0
	v_addc_co_u32_e32 v7, vcc, 0, v7, vcc
	s_nop 0
	v_add3_u32 v14, 16, v0, v5
	v_cvt_f32_i32_e32 v0, v4
	v_add_u32_e32 v10, 1, v4
	s_nop 0
	v_mul_f32_e32 v4, 0x39000000, v0
	v_sin_f32_e32 v6, v4
	v_cos_f32_e32 v0, v4
	s_waitcnt vmcnt(13)
	v_mov_b32_e32 v3, v228
	v_lshlrev_b32_e32 v4, 16, v3
	s_waitcnt vmcnt(12)
	v_mov_b32_e32 v11, v229
	v_lshlrev_b32_e32 v5, 16, v11
	v_pk_mul_f32 v[6:7], v[6:7], v[4:5] op_sel:[0,1] op_sel_hi:[0,0]
	s_nop 0
	v_pk_fma_f32 v[8:9], v[0:1], v[4:5], v[6:7]
	v_pk_fma_f32 v[12:13], v[0:1], v[4:5], v[6:7] op_sel_hi:[0,1,1] neg_lo:[0,0,1] neg_hi:[0,0,1]
	v_cvt_f32_i32_e32 v0, v10
	v_and_b32_e32 v7, 0xffff0000, v11
	v_mov_b32_e32 v9, v13
	v_mul_f32_e32 v6, 0x39000000, v0
	v_sin_f32_e32 v10, v6
	v_cos_f32_e32 v0, v6
	v_and_b32_e32 v6, 0xffff0000, v3
	ds_write_b128 v14, v[4:7]
	v_pk_mul_f32 v[4:5], v[10:11], v[6:7] op_sel:[0,1] op_sel_hi:[0,0]
	s_nop 0
	v_pk_fma_f32 v[10:11], v[0:1], v[6:7], v[4:5]
	v_pk_fma_f32 v[4:5], v[0:1], v[6:7], v[4:5] op_sel_hi:[0,1,1] neg_lo:[0,0,1] neg_hi:[0,0,1]
	v_add_u32_e32 v0, 0x400, v2
	v_mov_b32_e32 v11, v5
	v_mov_b32_e32 v2, v0
	ds_write_b128 v14, v[8:11] offset:32768
	s_nop 0
	v_cmp_lt_i32_e32 vcc, s31, v2
	s_nop 1
	v_cndmask_b32_e32 v0, 0, v154, vcc
	v_cndmask_b32_e32 v3, 0, v155, vcc
	v_add_u32_e32 v4, v0, v2
	v_lshlrev_b32_e32 v0, 1, v3
	v_lshl_add_u64 v[6:7], s[14:15], 0, v[0:1]
	v_ashrrev_i32_e32 v5, 31, v4
	v_lshl_add_u64 v[6:7], v[4:5], 1, v[6:7]
	v_lshlrev_b32_e32 v0, 3, v3
	s_nop 0
	v_add_co_u32_e32 v6, vcc, s24, v6
	v_lshlrev_b32_e32 v5, 3, v4
	s_nop 0
	v_addc_co_u32_e32 v7, vcc, 0, v7, vcc
	s_nop 0
	v_add3_u32 v14, 16, v0, v5
	v_cvt_f32_i32_e32 v0, v4
	v_add_u32_e32 v10, 1, v4
	s_nop 0
	v_mul_f32_e32 v4, 0x39000000, v0
	v_sin_f32_e32 v6, v4
	v_cos_f32_e32 v0, v4
	s_waitcnt vmcnt(11)
	v_mov_b32_e32 v3, v230
	v_lshlrev_b32_e32 v4, 16, v3
	s_waitcnt vmcnt(10)
	v_mov_b32_e32 v11, v231
	v_lshlrev_b32_e32 v5, 16, v11
	v_pk_mul_f32 v[6:7], v[6:7], v[4:5] op_sel:[0,1] op_sel_hi:[0,0]
	s_nop 0
	v_pk_fma_f32 v[8:9], v[0:1], v[4:5], v[6:7]
	v_pk_fma_f32 v[12:13], v[0:1], v[4:5], v[6:7] op_sel_hi:[0,1,1] neg_lo:[0,0,1] neg_hi:[0,0,1]
	v_cvt_f32_i32_e32 v0, v10
	v_and_b32_e32 v7, 0xffff0000, v11
	v_mov_b32_e32 v9, v13
	v_mul_f32_e32 v6, 0x39000000, v0
	v_sin_f32_e32 v10, v6
	v_cos_f32_e32 v0, v6
	v_and_b32_e32 v6, 0xffff0000, v3
	ds_write_b128 v14, v[4:7]
	v_pk_mul_f32 v[4:5], v[10:11], v[6:7] op_sel:[0,1] op_sel_hi:[0,0]
	s_nop 0
	v_pk_fma_f32 v[10:11], v[0:1], v[6:7], v[4:5]
	v_pk_fma_f32 v[4:5], v[0:1], v[6:7], v[4:5] op_sel_hi:[0,1,1] neg_lo:[0,0,1] neg_hi:[0,0,1]
	v_add_u32_e32 v0, 0x400, v2
	v_mov_b32_e32 v11, v5
	v_mov_b32_e32 v2, v0
	ds_write_b128 v14, v[8:11] offset:32768
	s_nop 0
	v_cmp_lt_i32_e32 vcc, s31, v2
	s_nop 1
	v_cndmask_b32_e32 v0, 0, v154, vcc
	v_cndmask_b32_e32 v3, 0, v155, vcc
	v_add_u32_e32 v4, v0, v2
	v_lshlrev_b32_e32 v0, 1, v3
	v_lshl_add_u64 v[6:7], s[14:15], 0, v[0:1]
	v_ashrrev_i32_e32 v5, 31, v4
	v_lshl_add_u64 v[6:7], v[4:5], 1, v[6:7]
	v_lshlrev_b32_e32 v0, 3, v3
	s_nop 0
	v_add_co_u32_e32 v6, vcc, s24, v6
	v_lshlrev_b32_e32 v5, 3, v4
	s_nop 0
	v_addc_co_u32_e32 v7, vcc, 0, v7, vcc
	s_nop 0
	v_add3_u32 v14, 16, v0, v5
	v_cvt_f32_i32_e32 v0, v4
	v_add_u32_e32 v10, 1, v4
	s_nop 0
	v_mul_f32_e32 v4, 0x39000000, v0
	v_sin_f32_e32 v6, v4
	v_cos_f32_e32 v0, v4
	s_waitcnt vmcnt(9)
	v_mov_b32_e32 v3, v232
	v_lshlrev_b32_e32 v4, 16, v3
	s_waitcnt vmcnt(8)
	v_mov_b32_e32 v11, v233
	v_lshlrev_b32_e32 v5, 16, v11
	v_pk_mul_f32 v[6:7], v[6:7], v[4:5] op_sel:[0,1] op_sel_hi:[0,0]
	s_nop 0
	v_pk_fma_f32 v[8:9], v[0:1], v[4:5], v[6:7]
	v_pk_fma_f32 v[12:13], v[0:1], v[4:5], v[6:7] op_sel_hi:[0,1,1] neg_lo:[0,0,1] neg_hi:[0,0,1]
	v_cvt_f32_i32_e32 v0, v10
	v_and_b32_e32 v7, 0xffff0000, v11
	v_mov_b32_e32 v9, v13
	v_mul_f32_e32 v6, 0x39000000, v0
	v_sin_f32_e32 v10, v6
	v_cos_f32_e32 v0, v6
	v_and_b32_e32 v6, 0xffff0000, v3
	ds_write_b128 v14, v[4:7]
	v_pk_mul_f32 v[4:5], v[10:11], v[6:7] op_sel:[0,1] op_sel_hi:[0,0]
	s_nop 0
	v_pk_fma_f32 v[10:11], v[0:1], v[6:7], v[4:5]
	v_pk_fma_f32 v[4:5], v[0:1], v[6:7], v[4:5] op_sel_hi:[0,1,1] neg_lo:[0,0,1] neg_hi:[0,0,1]
	v_add_u32_e32 v0, 0x400, v2
	v_mov_b32_e32 v11, v5
	v_mov_b32_e32 v2, v0
	ds_write_b128 v14, v[8:11] offset:32768
	s_nop 0
	v_cmp_lt_i32_e32 vcc, s31, v2
	s_nop 1
	v_cndmask_b32_e32 v0, 0, v154, vcc
	v_cndmask_b32_e32 v3, 0, v155, vcc
	v_add_u32_e32 v4, v0, v2
	v_lshlrev_b32_e32 v0, 1, v3
	v_lshl_add_u64 v[6:7], s[14:15], 0, v[0:1]
	v_ashrrev_i32_e32 v5, 31, v4
	v_lshl_add_u64 v[6:7], v[4:5], 1, v[6:7]
	v_lshlrev_b32_e32 v0, 3, v3
	s_nop 0
	v_add_co_u32_e32 v6, vcc, s24, v6
	v_lshlrev_b32_e32 v5, 3, v4
	s_nop 0
	v_addc_co_u32_e32 v7, vcc, 0, v7, vcc
	s_nop 0
	v_add3_u32 v14, 16, v0, v5
	v_cvt_f32_i32_e32 v0, v4
	v_add_u32_e32 v10, 1, v4
	s_nop 0
	v_mul_f32_e32 v4, 0x39000000, v0
	v_sin_f32_e32 v6, v4
	v_cos_f32_e32 v0, v4
	s_waitcnt vmcnt(7)
; DI float2 twid(float r) { return float2{__builtin_amdgcn_cosf(r), -__builtin_amdgcn_sinf(r)}; }
; DI void fftconv2_item(bft* x, const float2* kh) {
;     ...
;   for (int ii = 2 * tid; ii < 2 * L; ii += 2 * NTHR) { const int sel = ii >= L ? 1 : 0, i = ii - sel * L; bft* xa = x + sel * 2 * L; bft* xb = xa + L; float2* z = z0 + sel * N;
;     unsigned wa = *(const unsigned*)(xa + i), wb = *(const unsigned*)(xb + i);
;     float2 x0 = {__uint_as_float(wa << 16), __uint_as_float(wb << 16)}, x1 = {__uint_as_float(wa & 0xffff0000u), __uint_as_float(wb & 0xffff0000u)};
;     z[i] = x0; z[i + 1] = x1; z[L + i] = cmul(x0, twid((float)i * (1.f / N))); z[L + i + 1] = cmul(x1, twid((float)(i + 1) * (1.f / N))); }
	v_mov_b32_e32 v3, v234
	v_lshlrev_b32_e32 v4, 16, v3
	s_waitcnt vmcnt(6)
	v_mov_b32_e32 v11, v235
	v_lshlrev_b32_e32 v5, 16, v11
	v_pk_mul_f32 v[6:7], v[6:7], v[4:5] op_sel:[0,1] op_sel_hi:[0,0]
	s_nop 0
	v_pk_fma_f32 v[8:9], v[0:1], v[4:5], v[6:7]
	v_pk_fma_f32 v[12:13], v[0:1], v[4:5], v[6:7] op_sel_hi:[0,1,1] neg_lo:[0,0,1] neg_hi:[0,0,1]
	v_cvt_f32_i32_e32 v0, v10
	v_and_b32_e32 v7, 0xffff0000, v11
	v_mov_b32_e32 v9, v13
	v_mul_f32_e32 v6, 0x39000000, v0
	v_sin_f32_e32 v10, v6
	v_cos_f32_e32 v0, v6
	v_and_b32_e32 v6, 0xffff0000, v3
	ds_write_b128 v14, v[4:7]
	v_pk_mul_f32 v[4:5], v[10:11], v[6:7] op_sel:[0,1] op_sel_hi:[0,0]
	s_nop 0
	v_pk_fma_f32 v[10:11], v[0:1], v[6:7], v[4:5]
	v_pk_fma_f32 v[4:5], v[0:1], v[6:7], v[4:5] op_sel_hi:[0,1,1] neg_lo:[0,0,1] neg_hi:[0,0,1]
	v_add_u32_e32 v0, 0x400, v2
	v_mov_b32_e32 v11, v5
	v_mov_b32_e32 v2, v0
	ds_write_b128 v14, v[8:11] offset:32768
	s_nop 0
	v_cmp_lt_i32_e32 vcc, s31, v2
	s_nop 1
	v_cndmask_b32_e32 v0, 0, v154, vcc
	v_cndmask_b32_e32 v3, 0, v155, vcc
	v_add_u32_e32 v4, v0, v2
	v_lshlrev_b32_e32 v0, 1, v3
	v_lshl_add_u64 v[6:7], s[14:15], 0, v[0:1]
	v_ashrrev_i32_e32 v5, 31, v4
	v_lshl_add_u64 v[6:7], v[4:5], 1, v[6:7]
	v_lshlrev_b32_e32 v0, 3, v3
	s_nop 0
	v_add_co_u32_e32 v6, vcc, s24, v6
	v_lshlrev_b32_e32 v5, 3, v4
	s_nop 0
	v_addc_co_u32_e32 v7, vcc, 0, v7, vcc
	s_nop 0
	v_add3_u32 v14, 16, v0, v5
	v_cvt_f32_i32_e32 v0, v4
	v_add_u32_e32 v10, 1, v4
	s_nop 0
	v_mul_f32_e32 v4, 0x39000000, v0
	v_sin_f32_e32 v6, v4
	v_cos_f32_e32 v0, v4
	s_waitcnt vmcnt(5)
	v_mov_b32_e32 v3, v236
	v_lshlrev_b32_e32 v4, 16, v3
	s_waitcnt vmcnt(4)
	v_mov_b32_e32 v11, v237
	v_lshlrev_b32_e32 v5, 16, v11
	v_pk_mul_f32 v[6:7], v[6:7], v[4:5] op_sel:[0,1] op_sel_hi:[0,0]
	s_nop 0
	v_pk_fma_f32 v[8:9], v[0:1], v[4:5], v[6:7]
	v_pk_fma_f32 v[12:13], v[0:1], v[4:5], v[6:7] op_sel_hi:[0,1,1] neg_lo:[0,0,1] neg_hi:[0,0,1]
	v_cvt_f32_i32_e32 v0, v10
	v_and_b32_e32 v7, 0xffff0000, v11
	v_mov_b32_e32 v9, v13
	v_mul_f32_e32 v6, 0x39000000, v0
	v_sin_f32_e32 v10, v6
	v_cos_f32_e32 v0, v6
	v_and_b32_e32 v6, 0xffff0000, v3
	ds_write_b128 v14, v[4:7]
	v_pk_mul_f32 v[4:5], v[10:11], v[6:7] op_sel:[0,1] op_sel_hi:[0,0]
	s_nop 0
	v_pk_fma_f32 v[10:11], v[0:1], v[6:7], v[4:5]
	v_pk_fma_f32 v[4:5], v[0:1], v[6:7], v[4:5] op_sel_hi:[0,1,1] neg_lo:[0,0,1] neg_hi:[0,0,1]
	v_add_u32_e32 v0, 0x400, v2
	v_mov_b32_e32 v11, v5
	v_mov_b32_e32 v2, v0
	ds_write_b128 v14, v[8:11] offset:32768
	s_nop 0
	v_cmp_lt_i32_e32 vcc, s31, v2
	s_nop 1
	v_cndmask_b32_e32 v0, 0, v154, vcc
	v_cndmask_b32_e32 v3, 0, v155, vcc
	v_add_u32_e32 v4, v0, v2
	v_lshlrev_b32_e32 v0, 1, v3
	v_lshl_add_u64 v[6:7], s[14:15], 0, v[0:1]
	v_ashrrev_i32_e32 v5, 31, v4
	v_lshl_add_u64 v[6:7], v[4:5], 1, v[6:7]
	v_lshlrev_b32_e32 v0, 3, v3
	s_nop 0
	v_add_co_u32_e32 v6, vcc, s24, v6
	v_lshlrev_b32_e32 v5, 3, v4
	s_nop 0
	v_addc_co_u32_e32 v7, vcc, 0, v7, vcc
	s_nop 0
	v_add3_u32 v14, 16, v0, v5
	v_cvt_f32_i32_e32 v0, v4
	v_add_u32_e32 v10, 1, v4
	s_nop 0
	v_mul_f32_e32 v4, 0x39000000, v0
	v_sin_f32_e32 v6, v4
	v_cos_f32_e32 v0, v4
	s_waitcnt vmcnt(3)
	v_mov_b32_e32 v3, v238
	v_lshlrev_b32_e32 v4, 16, v3
	s_waitcnt vmcnt(2)
	v_mov_b32_e32 v11, v239
	v_lshlrev_b32_e32 v5, 16, v11
	v_pk_mul_f32 v[6:7], v[6:7], v[4:5] op_sel:[0,1] op_sel_hi:[0,0]
	s_nop 0
	v_pk_fma_f32 v[8:9], v[0:1], v[4:5], v[6:7]
	v_pk_fma_f32 v[12:13], v[0:1], v[4:5], v[6:7] op_sel_hi:[0,1,1] neg_lo:[0,0,1] neg_hi:[0,0,1]
	v_cvt_f32_i32_e32 v0, v10
	v_and_b32_e32 v7, 0xffff0000, v11
	v_mov_b32_e32 v9, v13
	v_mul_f32_e32 v6, 0x39000000, v0
	v_sin_f32_e32 v10, v6
	v_cos_f32_e32 v0, v6
	v_and_b32_e32 v6, 0xffff0000, v3
	ds_write_b128 v14, v[4:7]
	v_pk_mul_f32 v[4:5], v[10:11], v[6:7] op_sel:[0,1] op_sel_hi:[0,0]
	s_nop 0
	v_pk_fma_f32 v[10:11], v[0:1], v[6:7], v[4:5]
	v_pk_fma_f32 v[4:5], v[0:1], v[6:7], v[4:5] op_sel_hi:[0,1,1] neg_lo:[0,0,1] neg_hi:[0,0,1]
	v_add_u32_e32 v0, 0x400, v2
	v_mov_b32_e32 v11, v5
	v_mov_b32_e32 v2, v0
	ds_write_b128 v14, v[8:11] offset:32768
	s_nop 0
	v_cmp_lt_i32_e32 vcc, s31, v2
	s_nop 1
	v_cndmask_b32_e32 v0, 0, v154, vcc
	v_cndmask_b32_e32 v3, 0, v155, vcc
	v_add_u32_e32 v4, v0, v2
	v_lshlrev_b32_e32 v0, 1, v3
	v_lshl_add_u64 v[6:7], s[14:15], 0, v[0:1]
	v_ashrrev_i32_e32 v5, 31, v4
	v_lshl_add_u64 v[6:7], v[4:5], 1, v[6:7]
	v_lshlrev_b32_e32 v0, 3, v3
	s_nop 0
	v_add_co_u32_e32 v6, vcc, s24, v6
	v_lshlrev_b32_e32 v5, 3, v4
	s_nop 0
	v_addc_co_u32_e32 v7, vcc, 0, v7, vcc
	s_nop 0
	v_add3_u32 v14, 16, v0, v5
	v_cvt_f32_i32_e32 v0, v4
	v_add_u32_e32 v10, 1, v4
	s_nop 0
	v_mul_f32_e32 v4, 0x39000000, v0
	v_sin_f32_e32 v6, v4
	v_cos_f32_e32 v0, v4
	s_waitcnt vmcnt(1)
	v_mov_b32_e32 v3, v241
	v_lshlrev_b32_e32 v4, 16, v3
	s_waitcnt vmcnt(0)
	v_mov_b32_e32 v11, v242
	v_lshlrev_b32_e32 v5, 16, v11
	v_pk_mul_f32 v[6:7], v[6:7], v[4:5] op_sel:[0,1] op_sel_hi:[0,0]
	s_nop 0
	v_pk_fma_f32 v[8:9], v[0:1], v[4:5], v[6:7]
	v_pk_fma_f32 v[12:13], v[0:1], v[4:5], v[6:7] op_sel_hi:[0,1,1] neg_lo:[0,0,1] neg_hi:[0,0,1]
	v_cvt_f32_i32_e32 v0, v10
	v_and_b32_e32 v7, 0xffff0000, v11
	v_mov_b32_e32 v9, v13
	v_mul_f32_e32 v6, 0x39000000, v0
	v_sin_f32_e32 v10, v6
	v_cos_f32_e32 v0, v6
	v_and_b32_e32 v6, 0xffff0000, v3
	ds_write_b128 v14, v[4:7]
	v_pk_mul_f32 v[4:5], v[10:11], v[6:7] op_sel:[0,1] op_sel_hi:[0,0]
	s_nop 0
	v_pk_fma_f32 v[10:11], v[0:1], v[6:7], v[4:5]
	v_pk_fma_f32 v[4:5], v[0:1], v[6:7], v[4:5] op_sel_hi:[0,1,1] neg_lo:[0,0,1] neg_hi:[0,0,1]
	v_add_u32_e32 v0, 0x400, v2
	v_mov_b32_e32 v11, v5
	v_mov_b32_e32 v2, v0
	ds_write_b128 v14, v[8:11] offset:32768
	s_nop 0
	s_mov_b64 s[12:13], exec

; DI float2 twid(float r) { return float2{__builtin_amdgcn_cosf(r), -__builtin_amdgcn_sinf(r)}; }
; DI void bfly_fwd(float2 a0, float2 a1, float2 a2, float2 a3, float r, float2& o0, float2& o1, float2& o2, float2& o3) {
;   float2 t0 = {a0.x + a2.x, a0.y + a2.y}, t1 = {a0.x - a2.x, a0.y - a2.y}, t2 = {a1.x + a3.x, a1.y + a3.y}, t3 = {a1.x - a3.x, a1.y - a3.y};
;   float2 b0 = {t0.x + t2.x, t0.y + t2.y}, b2 = {t0.x - t2.x, t0.y - t2.y}, b1 = {t1.x + t3.y, t1.y - t3.x}, b3 = {t1.x - t3.y, t1.y + t3.x};
;   float2 w1 = twid(r), w2 = cmul(w1, w1), w3 = cmul(w2, w1);
;   o0 = b0; o1 = cmul(b1, w1); o2 = cmul(b2, w2); o3 = cmul(b3, w3);
; }
; template <int LOGN> DI void fftconv_item(bft* xa, bft* xb, const float2* kh) {
;     ...
;     constexpr int Q = N / 4; const float2 zero = {0.f, 0.f};
;     for (int i = 2 * tid; i < Q; i += 2 * NTHR) { unsigned wa = *(const unsigned*)(xa + i), wb = *(const unsigned*)(xb + i), wc = *(const unsigned*)(xa + Q + i), wd = *(const unsigned*)(xb + Q + i);
; #pragma unroll
;       for (int e = 0; e < 2; ++e) { float2 a0 = e ? float2{__uint_as_float(wa & 0xffff0000u), __uint_as_float(wb & 0xffff0000u)} : float2{__uint_as_float(wa << 16), __uint_as_float(wb << 16)};
;         float2 a1 = e ? float2{__uint_as_float(wc & 0xffff0000u), __uint_as_float(wd & 0xffff0000u)} : float2{__uint_as_float(wc << 16), __uint_as_float(wd << 16)};
;         float2 o0, o1, o2, o3; bfly_fwd(a0, a1, zero, zero, (float)(i + e) * (1.f / N), o0, o1, o2, o3);
;         z[i + e] = o0; z[i + e + Q] = o1; z[i + e + 2 * Q] = o2; z[i + e + 3 * Q] = o3; } }
.LBB0_1629:
	v_mov_b32_e32 v218, v4
	v_mov_b32_e32 v219, v5
	v_add_co_u32_e32 v220, vcc, 0x4000, v218
	global_load_dword v222, v[218:219], off
	s_nop 0
	v_addc_co_u32_e32 v221, vcc, 0, v219, vcc
	global_load_dword v223, v[220:221], off
	v_add_co_u32_e32 v220, vcc, 0x2000, v218
	s_nop 1
	v_addc_co_u32_e32 v221, vcc, 0, v219, vcc
	global_load_dword v224, v[220:221], off
	v_add_co_u32_e32 v220, vcc, 0x6000, v218
	s_nop 1
	v_addc_co_u32_e32 v221, vcc, 0, v219, vcc
	global_load_dword v225, v[220:221], off
	v_lshl_add_u64 v[218:219], v[218:219], 0, s[6:7]
	v_add_co_u32_e32 v220, vcc, 0x4000, v218
	global_load_dword v226, v[218:219], off
	s_nop 0
	v_addc_co_u32_e32 v221, vcc, 0, v219, vcc
	global_load_dword v227, v[220:221], off
	v_add_co_u32_e32 v220, vcc, 0x2000, v218
	s_nop 1
	v_addc_co_u32_e32 v221, vcc, 0, v219, vcc
	global_load_dword v228, v[220:221], off
	v_add_co_u32_e32 v220, vcc, 0x6000, v218
	s_nop 1
	v_addc_co_u32_e32 v221, vcc, 0, v219, vcc
	global_load_dword v229, v[220:221], off
	v_lshl_add_u64 v[218:219], v[218:219], 0, s[6:7]
	v_add_co_u32_e32 v220, vcc, 0x4000, v218
	global_load_dword v230, v[218:219], off
	s_nop 0
	v_addc_co_u32_e32 v221, vcc, 0, v219, vcc
	global_load_dword v231, v[220:221], off
	v_add_co_u32_e32 v220, vcc, 0x2000, v218
	s_nop 1
	v_addc_co_u32_e32 v221, vcc, 0, v219, vcc
	global_load_dword v232, v[220:221], off
	v_add_co_u32_e32 v220, vcc, 0x6000, v218
	s_nop 1
	v_addc_co_u32_e32 v221, vcc, 0, v219, vcc
	global_load_dword v233, v[220:221], off
	v_lshl_add_u64 v[218:219], v[218:219], 0, s[6:7]
	v_add_co_u32_e32 v220, vcc, 0x4000, v218
	global_load_dword v234, v[218:219], off
	s_nop 0
	v_addc_co_u32_e32 v221, vcc, 0, v219, vcc
	global_load_dword v235, v[220:221], off
	v_add_co_u32_e32 v220, vcc, 0x2000, v218
	s_nop 1
	v_addc_co_u32_e32 v221, vcc, 0, v219, vcc
	global_load_dword v236, v[220:221], off
	v_add_co_u32_e32 v220, vcc, 0x6000, v218
	s_nop 1
	v_addc_co_u32_e32 v221, vcc, 0, v219, vcc
	global_load_dword v237, v[220:221], off
	v_lshl_add_u64 v[218:219], v[218:219], 0, s[6:7]
	v_add_co_u32_e32 v8, vcc, 0x4000, v4
	s_nop 0
	v_addc_co_u32_e32 v9, vcc, 0, v5, vcc
	s_nop 0
	v_add_co_u32_e32 v8, vcc, 0x2000, v4
	v_add_u32_e32 v40, 0x10000, v6
	s_nop 0
	v_addc_co_u32_e32 v9, vcc, 0, v5, vcc
	s_nop 0
	v_add_co_u32_e32 v8, vcc, 0x6000, v4
	v_add_u32_e32 v41, 0x18000, v6
	s_nop 0
	v_addc_co_u32_e32 v9, vcc, 0, v5, vcc
	s_nop 0
	v_cvt_f32_i32_e32 v8, v7
	s_nop 0
	v_lshl_add_u64 v[4:5], v[4:5], 0, s[6:7]
	s_nop 0
	v_mul_f32_e32 v8, 0x38800000, v8
	v_sin_f32_e32 v14, v8
	v_cos_f32_e32 v10, v8
	v_xor_b32_e32 v11, 0x80000000, v14
	s_waitcnt vmcnt(15)
	v_mov_b32_e32 v32, v222
	v_lshlrev_b32_e32 v16, 16, v32
	s_waitcnt vmcnt(14)
	v_mov_b32_e32 v33, v223
	v_lshlrev_b32_e32 v17, 16, v33
	v_pk_add_f32 v[20:21], v[16:17], 0 op_sel_hi:[1,0]
	s_waitcnt vmcnt(13)
	v_mov_b32_e32 v34, v224
	v_lshlrev_b32_e32 v18, 16, v34
	s_waitcnt vmcnt(12)
	v_mov_b32_e32 v35, v225
	v_lshlrev_b32_e32 v19, 16, v35
	v_pk_add_f32 v[12:13], v[18:19], v[16:17] op_sel:[1,0] op_sel_hi:[0,1]
	v_pk_add_f32 v[24:25], v[16:17], v[18:19] op_sel:[0,1] op_sel_hi:[1,0] neg_lo:[0,1] neg_hi:[0,1]
	v_pk_add_f32 v[22:23], v[18:19], 0 op_sel_hi:[1,0]
	v_mov_b32_e32 v27, v25
	v_pk_mov_b32 v[24:25], v[24:25], v[12:13] op_sel:[1,0]
	v_pk_add_f32 v[8:9], v[20:21], v[22:23]
	v_pk_mul_f32 v[24:25], v[14:15], v[24:25] op_sel_hi:[0,1]
	v_pk_add_f32 v[22:23], v[20:21], v[22:23] neg_lo:[0,1] neg_hi:[0,1]
	v_mov_b32_e32 v15, v10
	v_mov_b32_e32 v20, v14
	v_mov_b32_e32 v21, v11
	v_mov_b32_e32 v26, v12
	v_pk_mul_f32 v[20:21], v[14:15], v[20:21]
	v_pk_fma_f32 v[12:13], v[10:11], v[12:13], v[24:25]
	v_pk_fma_f32 v[24:25], v[10:11], v[26:27], v[24:25] op_sel_hi:[0,1,1] neg_lo:[0,0,1] neg_hi:[0,0,1]
	v_pk_fma_f32 v[26:27], v[10:11], v[10:11], v[20:21] op_sel_hi:[0,1,1] neg_lo:[0,0,1] neg_hi:[0,0,1]
	v_pk_fma_f32 v[20:21], v[10:11], v[10:11], v[20:21] op_sel_hi:[0,1,1]
	s_nop 0
	v_pk_mov_b32 v[30:31], v[20:21], v[26:27] op_sel:[1,0]
	v_mov_b32_e32 v28, v26
	v_mov_b32_e32 v29, v21
	v_pk_mul_f32 v[14:15], v[14:15], v[30:31] op_sel_hi:[0,1]
	s_nop 0
	v_pk_fma_f32 v[30:31], v[10:11], v[28:29], v[14:15] op_sel_hi:[0,1,1]
	v_pk_fma_f32 v[10:11], v[10:11], v[28:29], v[14:15] op_sel_hi:[0,1,1] neg_lo:[0,0,1] neg_hi:[0,0,1]
	s_nop 0
	v_mov_b32_e32 v15, v11
	v_sub_f32_e32 v24, v16, v19
	v_add_f32_e32 v16, v17, v18
	v_pk_mov_b32 v[10:11], v[10:11], v[30:31] op_sel:[1,0]
	v_mov_b32_e32 v14, v30
	v_pk_mul_f32 v[10:11], v[16:17], v[10:11] op_sel_hi:[0,1]
	s_nop 0
	v_pk_fma_f32 v[16:17], v[24:25], v[30:31], v[10:11] op_sel_hi:[0,1,1] neg_lo:[0,0,1] neg_hi:[0,0,1]
	v_pk_fma_f32 v[28:29], v[24:25], v[14:15], v[10:11] op_sel_hi:[0,1,1]
	v_pk_mul_f32 v[10:11], v[20:21], v[22:23] op_sel:[1,1] op_sel_hi:[1,0]
	v_and_b32_e32 v31, 0xffff0000, v33
	v_pk_fma_f32 v[20:21], v[26:27], v[22:23], v[10:11] neg_lo:[0,0,1] neg_hi:[0,0,1]
	v_pk_fma_f32 v[26:27], v[26:27], v[22:23], v[10:11] op_sel_hi:[0,1,1]
	v_add_u32_e32 v10, 1, v7
	v_cvt_f32_i32_e32 v10, v10
	v_and_b32_e32 v30, 0xffff0000, v32
	v_and_b32_e32 v33, 0xffff0000, v35
	v_and_b32_e32 v32, 0xffff0000, v34
	v_mul_f32_e32 v10, 0x38800000, v10
	v_sin_f32_e32 v22, v10
	v_pk_add_f32 v[34:35], v[30:31], 0 op_sel_hi:[1,0]
	v_pk_add_f32 v[36:37], v[32:33], 0 op_sel_hi:[1,0]
	v_cos_f32_e32 v18, v10
	v_pk_add_f32 v[10:11], v[34:35], v[36:37]
	ds_write_b128 v6, v[8:11]
	v_pk_add_f32 v[8:9], v[32:33], v[30:31] op_sel:[1,0] op_sel_hi:[0,1]
	v_pk_add_f32 v[10:11], v[30:31], v[32:33] op_sel:[0,1] op_sel_hi:[1,0] neg_lo:[0,1] neg_hi:[0,1]
	v_xor_b32_e32 v19, 0x80000000, v22
	v_mov_b32_e32 v39, v11
	v_pk_mov_b32 v[10:11], v[10:11], v[8:9] op_sel:[1,0]
	v_mov_b32_e32 v38, v8
; DI float2 twid(float r) { return float2{__builtin_amdgcn_cosf(r), -__builtin_amdgcn_sinf(r)}; }
; DI void bfly_fwd(float2 a0, float2 a1, float2 a2, float2 a3, float r, float2& o0, float2& o1, float2& o2, float2& o3) {
;   float2 t0 = {a0.x + a2.x, a0.y + a2.y}, t1 = {a0.x - a2.x, a0.y - a2.y}, t2 = {a1.x + a3.x, a1.y + a3.y}, t3 = {a1.x - a3.x, a1.y - a3.y};
;   float2 b0 = {t0.x + t2.x, t0.y + t2.y}, b2 = {t0.x - t2.x, t0.y - t2.y}, b1 = {t1.x + t3.y, t1.y - t3.x}, b3 = {t1.x - t3.y, t1.y + t3.x};
;   float2 w1 = twid(r), w2 = cmul(w1, w1), w3 = cmul(w2, w1);
;   o0 = b0; o1 = cmul(b1, w1); o2 = cmul(b2, w2); o3 = cmul(b3, w3);
; }
; template <int LOGN> DI void fftconv_item(bft* xa, bft* xb, const float2* kh) {
;     ...
;     constexpr int Q = N / 4; const float2 zero = {0.f, 0.f};
;     for (int i = 2 * tid; i < Q; i += 2 * NTHR) { unsigned wa = *(const unsigned*)(xa + i), wb = *(const unsigned*)(xb + i), wc = *(const unsigned*)(xa + Q + i), wd = *(const unsigned*)(xb + Q + i);
; #pragma unroll
;       for (int e = 0; e < 2; ++e) { float2 a0 = e ? float2{__uint_as_float(wa & 0xffff0000u), __uint_as_float(wb & 0xffff0000u)} : float2{__uint_as_float(wa << 16), __uint_as_float(wb << 16)};
;         float2 a1 = e ? float2{__uint_as_float(wc & 0xffff0000u), __uint_as_float(wd & 0xffff0000u)} : float2{__uint_as_float(wc << 16), __uint_as_float(wd << 16)};
;         float2 o0, o1, o2, o3; bfly_fwd(a0, a1, zero, zero, (float)(i + e) * (1.f / N), o0, o1, o2, o3);
;         z[i + e] = o0; z[i + e + Q] = o1; z[i + e + 2 * Q] = o2; z[i + e + 3 * Q] = o3; } }
	v_pk_mul_f32 v[10:11], v[22:23], v[10:11] op_sel_hi:[0,1]
	s_nop 0
	v_pk_fma_f32 v[14:15], v[18:19], v[8:9], v[10:11]
	v_pk_fma_f32 v[8:9], v[18:19], v[38:39], v[10:11] op_sel_hi:[0,1,1] neg_lo:[0,0,1] neg_hi:[0,0,1]
	v_mov_b32_e32 v23, v18
	v_mov_b32_e32 v10, v22
	v_mov_b32_e32 v11, v19
	v_mov_b32_e32 v13, v25
	v_mov_b32_e32 v15, v9
	v_pk_mul_f32 v[10:11], v[22:23], v[10:11]
	ds_write_b128 v6, v[12:15] offset:32768
	v_pk_fma_f32 v[12:13], v[18:19], v[18:19], v[10:11] op_sel_hi:[0,1,1] neg_lo:[0,0,1] neg_hi:[0,0,1]
	v_pk_fma_f32 v[10:11], v[18:19], v[18:19], v[10:11] op_sel_hi:[0,1,1]
	s_nop 0
	v_pk_mov_b32 v[24:25], v[10:11], v[12:13] op_sel:[1,0]
	v_mov_b32_e32 v14, v12
	v_mov_b32_e32 v15, v11
	v_pk_mul_f32 v[22:23], v[22:23], v[24:25] op_sel_hi:[0,1]
	s_nop 0
	v_pk_fma_f32 v[24:25], v[18:19], v[14:15], v[22:23] op_sel_hi:[0,1,1]
	v_pk_fma_f32 v[14:15], v[18:19], v[14:15], v[22:23] op_sel_hi:[0,1,1] neg_lo:[0,0,1] neg_hi:[0,0,1]
	v_pk_add_f32 v[8:9], v[34:35], v[36:37] neg_lo:[0,1] neg_hi:[0,1]
	v_mov_b32_e32 v23, v15
	v_pk_add_f32 v[18:19], v[30:31], v[32:33] op_sel:[1,0] op_sel_hi:[1,0]
	v_pk_mov_b32 v[14:15], v[14:15], v[24:25] op_sel:[1,0]
	v_mov_b32_e32 v22, v24
	v_pk_add_f32 v[34:35], v[30:31], v[32:33] op_sel:[0,1] op_sel_hi:[0,1] neg_lo:[0,1] neg_hi:[0,1]
	v_pk_mul_f32 v[14:15], v[18:19], v[14:15]
	v_pk_mul_f32 v[10:11], v[10:11], v[8:9] op_sel:[1,1] op_sel_hi:[1,0]
	v_pk_fma_f32 v[18:19], v[34:35], v[24:25], v[14:15] neg_lo:[0,0,1] neg_hi:[0,0,1]
	v_pk_fma_f32 v[14:15], v[34:35], v[22:23], v[14:15]
	v_pk_fma_f32 v[22:23], v[12:13], v[8:9], v[10:11] neg_lo:[0,0,1] neg_hi:[0,0,1]
	v_pk_fma_f32 v[8:9], v[12:13], v[8:9], v[10:11] op_sel_hi:[0,1,1]
	s_nop 0
	v_add_u32_e32 v8, 0x400, v7
	v_mov_b32_e32 v21, v27
	v_mov_b32_e32 v23, v9
	v_mov_b32_e32 v17, v29
	v_mov_b32_e32 v19, v15
	v_add_u32_e32 v6, 0x2000, v6
	v_mov_b32_e32 v7, v8
	ds_write_b128 v40, v[20:23]
	ds_write_b128 v41, v[16:19]
	s_nop 0
	v_add_co_u32_e32 v8, vcc, 0x4000, v4
	s_nop 0
	v_addc_co_u32_e32 v9, vcc, 0, v5, vcc
	s_nop 0
	v_add_co_u32_e32 v8, vcc, 0x2000, v4
	v_add_u32_e32 v40, 0x10000, v6
	s_nop 0
	v_addc_co_u32_e32 v9, vcc, 0, v5, vcc
	s_nop 0
	v_add_co_u32_e32 v8, vcc, 0x6000, v4
	v_add_u32_e32 v41, 0x18000, v6
	s_nop 0
	v_addc_co_u32_e32 v9, vcc, 0, v5, vcc
	s_nop 0
	v_cvt_f32_i32_e32 v8, v7
	s_nop 0
	v_lshl_add_u64 v[4:5], v[4:5], 0, s[6:7]
	s_nop 0
	v_mul_f32_e32 v8, 0x38800000, v8
	v_sin_f32_e32 v14, v8
	v_cos_f32_e32 v10, v8
	v_xor_b32_e32 v11, 0x80000000, v14
	s_waitcnt vmcnt(11)
	v_mov_b32_e32 v32, v226
	v_lshlrev_b32_e32 v16, 16, v32
	s_waitcnt vmcnt(10)
	v_mov_b32_e32 v33, v227
	v_lshlrev_b32_e32 v17, 16, v33
	v_pk_add_f32 v[20:21], v[16:17], 0 op_sel_hi:[1,0]
	s_waitcnt vmcnt(9)
	v_mov_b32_e32 v34, v228
	v_lshlrev_b32_e32 v18, 16, v34
	s_waitcnt vmcnt(8)
	v_mov_b32_e32 v35, v229
	v_lshlrev_b32_e32 v19, 16, v35
	v_pk_add_f32 v[12:13], v[18:19], v[16:17] op_sel:[1,0] op_sel_hi:[0,1]
	v_pk_add_f32 v[24:25], v[16:17], v[18:19] op_sel:[0,1] op_sel_hi:[1,0] neg_lo:[0,1] neg_hi:[0,1]
	v_pk_add_f32 v[22:23], v[18:19], 0 op_sel_hi:[1,0]
	v_mov_b32_e32 v27, v25
	v_pk_mov_b32 v[24:25], v[24:25], v[12:13] op_sel:[1,0]
	v_pk_add_f32 v[8:9], v[20:21], v[22:23]
	v_pk_mul_f32 v[24:25], v[14:15], v[24:25] op_sel_hi:[0,1]
	v_pk_add_f32 v[22:23], v[20:21], v[22:23] neg_lo:[0,1] neg_hi:[0,1]
	v_mov_b32_e32 v15, v10
	v_mov_b32_e32 v20, v14
	v_mov_b32_e32 v21, v11
	v_mov_b32_e32 v26, v12
	v_pk_mul_f32 v[20:21], v[14:15], v[20:21]
	v_pk_fma_f32 v[12:13], v[10:11], v[12:13], v[24:25]
	v_pk_fma_f32 v[24:25], v[10:11], v[26:27], v[24:25] op_sel_hi:[0,1,1] neg_lo:[0,0,1] neg_hi:[0,0,1]
	v_pk_fma_f32 v[26:27], v[10:11], v[10:11], v[20:21] op_sel_hi:[0,1,1] neg_lo:[0,0,1] neg_hi:[0,0,1]
	v_pk_fma_f32 v[20:21], v[10:11], v[10:11], v[20:21] op_sel_hi:[0,1,1]
	s_nop 0
	v_pk_mov_b32 v[30:31], v[20:21], v[26:27] op_sel:[1,0]
	v_mov_b32_e32 v28, v26
	v_mov_b32_e32 v29, v21
	v_pk_mul_f32 v[14:15], v[14:15], v[30:31] op_sel_hi:[0,1]
	s_nop 0
	v_pk_fma_f32 v[30:31], v[10:11], v[28:29], v[14:15] op_sel_hi:[0,1,1]
	v_pk_fma_f32 v[10:11], v[10:11], v[28:29], v[14:15] op_sel_hi:[0,1,1] neg_lo:[0,0,1] neg_hi:[0,0,1]
	s_nop 0
	v_mov_b32_e32 v15, v11
	v_sub_f32_e32 v24, v16, v19
	v_add_f32_e32 v16, v17, v18
	v_pk_mov_b32 v[10:11], v[10:11], v[30:31] op_sel:[1,0]
	v_mov_b32_e32 v14, v30
	v_pk_mul_f32 v[10:11], v[16:17], v[10:11] op_sel_hi:[0,1]
	s_nop 0
	v_pk_fma_f32 v[16:17], v[24:25], v[30:31], v[10:11] op_sel_hi:[0,1,1] neg_lo:[0,0,1] neg_hi:[0,0,1]
	v_pk_fma_f32 v[28:29], v[24:25], v[14:15], v[10:11] op_sel_hi:[0,1,1]
	v_pk_mul_f32 v[10:11], v[20:21], v[22:23] op_sel:[1,1] op_sel_hi:[1,0]
	v_and_b32_e32 v31, 0xffff0000, v33
	v_pk_fma_f32 v[20:21], v[26:27], v[22:23], v[10:11] neg_lo:[0,0,1] neg_hi:[0,0,1]
	v_pk_fma_f32 v[26:27], v[26:27], v[22:23], v[10:11] op_sel_hi:[0,1,1]
	v_add_u32_e32 v10, 1, v7
	v_cvt_f32_i32_e32 v10, v10
	v_and_b32_e32 v30, 0xffff0000, v32
	v_and_b32_e32 v33, 0xffff0000, v35
	v_and_b32_e32 v32, 0xffff0000, v34
	v_mul_f32_e32 v10, 0x38800000, v10
	v_sin_f32_e32 v22, v10
	v_pk_add_f32 v[34:35], v[30:31], 0 op_sel_hi:[1,0]
	v_pk_add_f32 v[36:37], v[32:33], 0 op_sel_hi:[1,0]
	v_cos_f32_e32 v18, v10
	v_pk_add_f32 v[10:11], v[34:35], v[36:37]
	ds_write_b128 v6, v[8:11]
	v_pk_add_f32 v[8:9], v[32:33], v[30:31] op_sel:[1,0] op_sel_hi:[0,1]
	v_pk_add_f32 v[10:11], v[30:31], v[32:33] op_sel:[0,1] op_sel_hi:[1,0] neg_lo:[0,1] neg_hi:[0,1]
	v_xor_b32_e32 v19, 0x80000000, v22
	v_mov_b32_e32 v39, v11
	v_pk_mov_b32 v[10:11], v[10:11], v[8:9] op_sel:[1,0]
	v_mov_b32_e32 v38, v8
	v_pk_mul_f32 v[10:11], v[22:23], v[10:11] op_sel_hi:[0,1]
	s_nop 0
	v_pk_fma_f32 v[14:15], v[18:19], v[8:9], v[10:11]
; DI float2 twid(float r) { return float2{__builtin_amdgcn_cosf(r), -__builtin_amdgcn_sinf(r)}; }
; DI void bfly_fwd(float2 a0, float2 a1, float2 a2, float2 a3, float r, float2& o0, float2& o1, float2& o2, float2& o3) {
;   float2 t0 = {a0.x + a2.x, a0.y + a2.y}, t1 = {a0.x - a2.x, a0.y - a2.y}, t2 = {a1.x + a3.x, a1.y + a3.y}, t3 = {a1.x - a3.x, a1.y - a3.y};
;   float2 b0 = {t0.x + t2.x, t0.y + t2.y}, b2 = {t0.x - t2.x, t0.y - t2.y}, b1 = {t1.x + t3.y, t1.y - t3.x}, b3 = {t1.x - t3.y, t1.y + t3.x};
;   float2 w1 = twid(r), w2 = cmul(w1, w1), w3 = cmul(w2, w1);
;   o0 = b0; o1 = cmul(b1, w1); o2 = cmul(b2, w2); o3 = cmul(b3, w3);
; }
; template <int LOGN> DI void fftconv_item(bft* xa, bft* xb, const float2* kh) {
;     ...
;     constexpr int Q = N / 4; const float2 zero = {0.f, 0.f};
;     for (int i = 2 * tid; i < Q; i += 2 * NTHR) { unsigned wa = *(const unsigned*)(xa + i), wb = *(const unsigned*)(xb + i), wc = *(const unsigned*)(xa + Q + i), wd = *(const unsigned*)(xb + Q + i);
; #pragma unroll
;       for (int e = 0; e < 2; ++e) { float2 a0 = e ? float2{__uint_as_float(wa & 0xffff0000u), __uint_as_float(wb & 0xffff0000u)} : float2{__uint_as_float(wa << 16), __uint_as_float(wb << 16)};
;         float2 a1 = e ? float2{__uint_as_float(wc & 0xffff0000u), __uint_as_float(wd & 0xffff0000u)} : float2{__uint_as_float(wc << 16), __uint_as_float(wd << 16)};
;         float2 o0, o1, o2, o3; bfly_fwd(a0, a1, zero, zero, (float)(i + e) * (1.f / N), o0, o1, o2, o3);
;         z[i + e] = o0; z[i + e + Q] = o1; z[i + e + 2 * Q] = o2; z[i + e + 3 * Q] = o3; } }
	v_pk_fma_f32 v[8:9], v[18:19], v[38:39], v[10:11] op_sel_hi:[0,1,1] neg_lo:[0,0,1] neg_hi:[0,0,1]
	v_mov_b32_e32 v23, v18
	v_mov_b32_e32 v10, v22
	v_mov_b32_e32 v11, v19
	v_mov_b32_e32 v13, v25
	v_mov_b32_e32 v15, v9
	v_pk_mul_f32 v[10:11], v[22:23], v[10:11]
	ds_write_b128 v6, v[12:15] offset:32768
	v_pk_fma_f32 v[12:13], v[18:19], v[18:19], v[10:11] op_sel_hi:[0,1,1] neg_lo:[0,0,1] neg_hi:[0,0,1]
	v_pk_fma_f32 v[10:11], v[18:19], v[18:19], v[10:11] op_sel_hi:[0,1,1]
	s_nop 0
	v_pk_mov_b32 v[24:25], v[10:11], v[12:13] op_sel:[1,0]
	v_mov_b32_e32 v14, v12
	v_mov_b32_e32 v15, v11
	v_pk_mul_f32 v[22:23], v[22:23], v[24:25] op_sel_hi:[0,1]
	s_nop 0
	v_pk_fma_f32 v[24:25], v[18:19], v[14:15], v[22:23] op_sel_hi:[0,1,1]
	v_pk_fma_f32 v[14:15], v[18:19], v[14:15], v[22:23] op_sel_hi:[0,1,1] neg_lo:[0,0,1] neg_hi:[0,0,1]
	v_pk_add_f32 v[8:9], v[34:35], v[36:37] neg_lo:[0,1] neg_hi:[0,1]
	v_mov_b32_e32 v23, v15
	v_pk_add_f32 v[18:19], v[30:31], v[32:33] op_sel:[1,0] op_sel_hi:[1,0]
	v_pk_mov_b32 v[14:15], v[14:15], v[24:25] op_sel:[1,0]
	v_mov_b32_e32 v22, v24
	v_pk_add_f32 v[34:35], v[30:31], v[32:33] op_sel:[0,1] op_sel_hi:[0,1] neg_lo:[0,1] neg_hi:[0,1]
	v_pk_mul_f32 v[14:15], v[18:19], v[14:15]
	v_pk_mul_f32 v[10:11], v[10:11], v[8:9] op_sel:[1,1] op_sel_hi:[1,0]
	v_pk_fma_f32 v[18:19], v[34:35], v[24:25], v[14:15] neg_lo:[0,0,1] neg_hi:[0,0,1]
	v_pk_fma_f32 v[14:15], v[34:35], v[22:23], v[14:15]
	v_pk_fma_f32 v[22:23], v[12:13], v[8:9], v[10:11] neg_lo:[0,0,1] neg_hi:[0,0,1]
	v_pk_fma_f32 v[8:9], v[12:13], v[8:9], v[10:11] op_sel_hi:[0,1,1]
	s_nop 0
	v_add_u32_e32 v8, 0x400, v7
	v_mov_b32_e32 v21, v27
	v_mov_b32_e32 v23, v9
	v_mov_b32_e32 v17, v29
	v_mov_b32_e32 v19, v15
	v_add_u32_e32 v6, 0x2000, v6
	v_mov_b32_e32 v7, v8
	ds_write_b128 v40, v[20:23]
	ds_write_b128 v41, v[16:19]
	s_nop 0
	v_add_co_u32_e32 v8, vcc, 0x4000, v4
	s_nop 0
	v_addc_co_u32_e32 v9, vcc, 0, v5, vcc
	s_nop 0
	v_add_co_u32_e32 v8, vcc, 0x2000, v4
	v_add_u32_e32 v40, 0x10000, v6
	s_nop 0
	v_addc_co_u32_e32 v9, vcc, 0, v5, vcc
	s_nop 0
	v_add_co_u32_e32 v8, vcc, 0x6000, v4
	v_add_u32_e32 v41, 0x18000, v6
	s_nop 0
	v_addc_co_u32_e32 v9, vcc, 0, v5, vcc
	s_nop 0
	v_cvt_f32_i32_e32 v8, v7
	s_nop 0
	v_lshl_add_u64 v[4:5], v[4:5], 0, s[6:7]
	s_nop 0
	v_mul_f32_e32 v8, 0x38800000, v8
	v_sin_f32_e32 v14, v8
	v_cos_f32_e32 v10, v8
	v_xor_b32_e32 v11, 0x80000000, v14
	s_waitcnt vmcnt(7)
	v_mov_b32_e32 v32, v230
	v_lshlrev_b32_e32 v16, 16, v32
	s_waitcnt vmcnt(6)
	v_mov_b32_e32 v33, v231
	v_lshlrev_b32_e32 v17, 16, v33
	v_pk_add_f32 v[20:21], v[16:17], 0 op_sel_hi:[1,0]
	s_waitcnt vmcnt(5)
	v_mov_b32_e32 v34, v232
	v_lshlrev_b32_e32 v18, 16, v34
	s_waitcnt vmcnt(4)
	v_mov_b32_e32 v35, v233
	v_lshlrev_b32_e32 v19, 16, v35
	v_pk_add_f32 v[12:13], v[18:19], v[16:17] op_sel:[1,0] op_sel_hi:[0,1]
	v_pk_add_f32 v[24:25], v[16:17], v[18:19] op_sel:[0,1] op_sel_hi:[1,0] neg_lo:[0,1] neg_hi:[0,1]
	v_pk_add_f32 v[22:23], v[18:19], 0 op_sel_hi:[1,0]
	v_mov_b32_e32 v27, v25
	v_pk_mov_b32 v[24:25], v[24:25], v[12:13] op_sel:[1,0]
	v_pk_add_f32 v[8:9], v[20:21], v[22:23]
	v_pk_mul_f32 v[24:25], v[14:15], v[24:25] op_sel_hi:[0,1]
	v_pk_add_f32 v[22:23], v[20:21], v[22:23] neg_lo:[0,1] neg_hi:[0,1]
	v_mov_b32_e32 v15, v10
	v_mov_b32_e32 v20, v14
	v_mov_b32_e32 v21, v11
	v_mov_b32_e32 v26, v12
	v_pk_mul_f32 v[20:21], v[14:15], v[20:21]
	v_pk_fma_f32 v[12:13], v[10:11], v[12:13], v[24:25]
	v_pk_fma_f32 v[24:25], v[10:11], v[26:27], v[24:25] op_sel_hi:[0,1,1] neg_lo:[0,0,1] neg_hi:[0,0,1]
	v_pk_fma_f32 v[26:27], v[10:11], v[10:11], v[20:21] op_sel_hi:[0,1,1] neg_lo:[0,0,1] neg_hi:[0,0,1]
	v_pk_fma_f32 v[20:21], v[10:11], v[10:11], v[20:21] op_sel_hi:[0,1,1]
	s_nop 0
	v_pk_mov_b32 v[30:31], v[20:21], v[26:27] op_sel:[1,0]
	v_mov_b32_e32 v28, v26
	v_mov_b32_e32 v29, v21
	v_pk_mul_f32 v[14:15], v[14:15], v[30:31] op_sel_hi:[0,1]
	s_nop 0
	v_pk_fma_f32 v[30:31], v[10:11], v[28:29], v[14:15] op_sel_hi:[0,1,1]
	v_pk_fma_f32 v[10:11], v[10:11], v[28:29], v[14:15] op_sel_hi:[0,1,1] neg_lo:[0,0,1] neg_hi:[0,0,1]
	s_nop 0
	v_mov_b32_e32 v15, v11
	v_sub_f32_e32 v24, v16, v19
	v_add_f32_e32 v16, v17, v18
	v_pk_mov_b32 v[10:11], v[10:11], v[30:31] op_sel:[1,0]
	v_mov_b32_e32 v14, v30
	v_pk_mul_f32 v[10:11], v[16:17], v[10:11] op_sel_hi:[0,1]
	s_nop 0
	v_pk_fma_f32 v[16:17], v[24:25], v[30:31], v[10:11] op_sel_hi:[0,1,1] neg_lo:[0,0,1] neg_hi:[0,0,1]
	v_pk_fma_f32 v[28:29], v[24:25], v[14:15], v[10:11] op_sel_hi:[0,1,1]
	v_pk_mul_f32 v[10:11], v[20:21], v[22:23] op_sel:[1,1] op_sel_hi:[1,0]
	v_and_b32_e32 v31, 0xffff0000, v33
	v_pk_fma_f32 v[20:21], v[26:27], v[22:23], v[10:11] neg_lo:[0,0,1] neg_hi:[0,0,1]
	v_pk_fma_f32 v[26:27], v[26:27], v[22:23], v[10:11] op_sel_hi:[0,1,1]
	v_add_u32_e32 v10, 1, v7
	v_cvt_f32_i32_e32 v10, v10
	v_and_b32_e32 v30, 0xffff0000, v32
	v_and_b32_e32 v33, 0xffff0000, v35
	v_and_b32_e32 v32, 0xffff0000, v34
	v_mul_f32_e32 v10, 0x38800000, v10
	v_sin_f32_e32 v22, v10
	v_pk_add_f32 v[34:35], v[30:31], 0 op_sel_hi:[1,0]
	v_pk_add_f32 v[36:37], v[32:33], 0 op_sel_hi:[1,0]
	v_cos_f32_e32 v18, v10
	v_pk_add_f32 v[10:11], v[34:35], v[36:37]
	ds_write_b128 v6, v[8:11]
	v_pk_add_f32 v[8:9], v[32:33], v[30:31] op_sel:[1,0] op_sel_hi:[0,1]
	v_pk_add_f32 v[10:11], v[30:31], v[32:33] op_sel:[0,1] op_sel_hi:[1,0] neg_lo:[0,1] neg_hi:[0,1]
	v_xor_b32_e32 v19, 0x80000000, v22
	v_mov_b32_e32 v39, v11
	v_pk_mov_b32 v[10:11], v[10:11], v[8:9] op_sel:[1,0]
	v_mov_b32_e32 v38, v8
	v_pk_mul_f32 v[10:11], v[22:23], v[10:11] op_sel_hi:[0,1]
	s_nop 0
	v_pk_fma_f32 v[14:15], v[18:19], v[8:9], v[10:11]
	v_pk_fma_f32 v[8:9], v[18:19], v[38:39], v[10:11] op_sel_hi:[0,1,1] neg_lo:[0,0,1] neg_hi:[0,0,1]
; DI float2 twid(float r) { return float2{__builtin_amdgcn_cosf(r), -__builtin_amdgcn_sinf(r)}; }
; DI void bfly_fwd(float2 a0, float2 a1, float2 a2, float2 a3, float r, float2& o0, float2& o1, float2& o2, float2& o3) {
;   float2 t0 = {a0.x + a2.x, a0.y + a2.y}, t1 = {a0.x - a2.x, a0.y - a2.y}, t2 = {a1.x + a3.x, a1.y + a3.y}, t3 = {a1.x - a3.x, a1.y - a3.y};
;   float2 b0 = {t0.x + t2.x, t0.y + t2.y}, b2 = {t0.x - t2.x, t0.y - t2.y}, b1 = {t1.x + t3.y, t1.y - t3.x}, b3 = {t1.x - t3.y, t1.y + t3.x};
;   float2 w1 = twid(r), w2 = cmul(w1, w1), w3 = cmul(w2, w1);
;   o0 = b0; o1 = cmul(b1, w1); o2 = cmul(b2, w2); o3 = cmul(b3, w3);
; }
; template <int LOGN> DI void fftconv_item(bft* xa, bft* xb, const float2* kh) {
;     ...
;     constexpr int Q = N / 4; const float2 zero = {0.f, 0.f};
;     for (int i = 2 * tid; i < Q; i += 2 * NTHR) { unsigned wa = *(const unsigned*)(xa + i), wb = *(const unsigned*)(xb + i), wc = *(const unsigned*)(xa + Q + i), wd = *(const unsigned*)(xb + Q + i);
; #pragma unroll
;       for (int e = 0; e < 2; ++e) { float2 a0 = e ? float2{__uint_as_float(wa & 0xffff0000u), __uint_as_float(wb & 0xffff0000u)} : float2{__uint_as_float(wa << 16), __uint_as_float(wb << 16)};
;         float2 a1 = e ? float2{__uint_as_float(wc & 0xffff0000u), __uint_as_float(wd & 0xffff0000u)} : float2{__uint_as_float(wc << 16), __uint_as_float(wd << 16)};
;         float2 o0, o1, o2, o3; bfly_fwd(a0, a1, zero, zero, (float)(i + e) * (1.f / N), o0, o1, o2, o3);
;         z[i + e] = o0; z[i + e + Q] = o1; z[i + e + 2 * Q] = o2; z[i + e + 3 * Q] = o3; } }
	v_mov_b32_e32 v23, v18
	v_mov_b32_e32 v10, v22
	v_mov_b32_e32 v11, v19
	v_mov_b32_e32 v13, v25
	v_mov_b32_e32 v15, v9
	v_pk_mul_f32 v[10:11], v[22:23], v[10:11]
	ds_write_b128 v6, v[12:15] offset:32768
	v_pk_fma_f32 v[12:13], v[18:19], v[18:19], v[10:11] op_sel_hi:[0,1,1] neg_lo:[0,0,1] neg_hi:[0,0,1]
	v_pk_fma_f32 v[10:11], v[18:19], v[18:19], v[10:11] op_sel_hi:[0,1,1]
	s_nop 0
	v_pk_mov_b32 v[24:25], v[10:11], v[12:13] op_sel:[1,0]
	v_mov_b32_e32 v14, v12
	v_mov_b32_e32 v15, v11
	v_pk_mul_f32 v[22:23], v[22:23], v[24:25] op_sel_hi:[0,1]
	s_nop 0
	v_pk_fma_f32 v[24:25], v[18:19], v[14:15], v[22:23] op_sel_hi:[0,1,1]
	v_pk_fma_f32 v[14:15], v[18:19], v[14:15], v[22:23] op_sel_hi:[0,1,1] neg_lo:[0,0,1] neg_hi:[0,0,1]
	v_pk_add_f32 v[8:9], v[34:35], v[36:37] neg_lo:[0,1] neg_hi:[0,1]
	v_mov_b32_e32 v23, v15
	v_pk_add_f32 v[18:19], v[30:31], v[32:33] op_sel:[1,0] op_sel_hi:[1,0]
	v_pk_mov_b32 v[14:15], v[14:15], v[24:25] op_sel:[1,0]
	v_mov_b32_e32 v22, v24
	v_pk_add_f32 v[34:35], v[30:31], v[32:33] op_sel:[0,1] op_sel_hi:[0,1] neg_lo:[0,1] neg_hi:[0,1]
	v_pk_mul_f32 v[14:15], v[18:19], v[14:15]
	v_pk_mul_f32 v[10:11], v[10:11], v[8:9] op_sel:[1,1] op_sel_hi:[1,0]
	v_pk_fma_f32 v[18:19], v[34:35], v[24:25], v[14:15] neg_lo:[0,0,1] neg_hi:[0,0,1]
	v_pk_fma_f32 v[14:15], v[34:35], v[22:23], v[14:15]
	v_pk_fma_f32 v[22:23], v[12:13], v[8:9], v[10:11] neg_lo:[0,0,1] neg_hi:[0,0,1]
	v_pk_fma_f32 v[8:9], v[12:13], v[8:9], v[10:11] op_sel_hi:[0,1,1]
	s_nop 0
	v_add_u32_e32 v8, 0x400, v7
	v_mov_b32_e32 v21, v27
	v_mov_b32_e32 v23, v9
	v_mov_b32_e32 v17, v29
	v_mov_b32_e32 v19, v15
	v_add_u32_e32 v6, 0x2000, v6
	v_mov_b32_e32 v7, v8
	ds_write_b128 v40, v[20:23]
	ds_write_b128 v41, v[16:19]
	s_nop 0
	v_add_co_u32_e32 v8, vcc, 0x4000, v4
	s_nop 0
	v_addc_co_u32_e32 v9, vcc, 0, v5, vcc
	s_nop 0
	v_add_co_u32_e32 v8, vcc, 0x2000, v4
	v_add_u32_e32 v40, 0x10000, v6
	s_nop 0
	v_addc_co_u32_e32 v9, vcc, 0, v5, vcc
	s_nop 0
	v_add_co_u32_e32 v8, vcc, 0x6000, v4
	v_add_u32_e32 v41, 0x18000, v6
	s_nop 0
	v_addc_co_u32_e32 v9, vcc, 0, v5, vcc
	s_nop 0
	v_cvt_f32_i32_e32 v8, v7
	s_nop 0
	v_lshl_add_u64 v[4:5], v[4:5], 0, s[6:7]
	s_nop 0
	v_mul_f32_e32 v8, 0x38800000, v8
	v_sin_f32_e32 v14, v8
	v_cos_f32_e32 v10, v8
	v_xor_b32_e32 v11, 0x80000000, v14
	s_waitcnt vmcnt(3)
	v_mov_b32_e32 v32, v234
	v_lshlrev_b32_e32 v16, 16, v32
	s_waitcnt vmcnt(2)
	v_mov_b32_e32 v33, v235
	v_lshlrev_b32_e32 v17, 16, v33
	v_pk_add_f32 v[20:21], v[16:17], 0 op_sel_hi:[1,0]
	s_waitcnt vmcnt(1)
	v_mov_b32_e32 v34, v236
	v_lshlrev_b32_e32 v18, 16, v34
	s_waitcnt vmcnt(0)
; DI float2 twid(float r) { return float2{__builtin_amdgcn_cosf(r), -__builtin_amdgcn_sinf(r)}; }
; DI void bfly_fwd(float2 a0, float2 a1, float2 a2, float2 a3, float r, float2& o0, float2& o1, float2& o2, float2& o3) {
;   float2 t0 = {a0.x + a2.x, a0.y + a2.y}, t1 = {a0.x - a2.x, a0.y - a2.y}, t2 = {a1.x + a3.x, a1.y + a3.y}, t3 = {a1.x - a3.x, a1.y - a3.y};
;   float2 b0 = {t0.x + t2.x, t0.y + t2.y}, b2 = {t0.x - t2.x, t0.y - t2.y}, b1 = {t1.x + t3.y, t1.y - t3.x}, b3 = {t1.x - t3.y, t1.y + t3.x};
;   float2 w1 = twid(r), w2 = cmul(w1, w1), w3 = cmul(w2, w1);
;   o0 = b0; o1 = cmul(b1, w1); o2 = cmul(b2, w2); o3 = cmul(b3, w3);
; }
; template <int LOGN> DI void fftconv_item(bft* xa, bft* xb, const float2* kh) {
;     ...
;     constexpr int Q = N / 4; const float2 zero = {0.f, 0.f};
;     for (int i = 2 * tid; i < Q; i += 2 * NTHR) { unsigned wa = *(const unsigned*)(xa + i), wb = *(const unsigned*)(xb + i), wc = *(const unsigned*)(xa + Q + i), wd = *(const unsigned*)(xb + Q + i);
; #pragma unroll
;       for (int e = 0; e < 2; ++e) { float2 a0 = e ? float2{__uint_as_float(wa & 0xffff0000u), __uint_as_float(wb & 0xffff0000u)} : float2{__uint_as_float(wa << 16), __uint_as_float(wb << 16)};
;         float2 a1 = e ? float2{__uint_as_float(wc & 0xffff0000u), __uint_as_float(wd & 0xffff0000u)} : float2{__uint_as_float(wc << 16), __uint_as_float(wd << 16)};
;         float2 o0, o1, o2, o3; bfly_fwd(a0, a1, zero, zero, (float)(i + e) * (1.f / N), o0, o1, o2, o3);
;         z[i + e] = o0; z[i + e + Q] = o1; z[i + e + 2 * Q] = o2; z[i + e + 3 * Q] = o3; } }
	v_mov_b32_e32 v35, v237
	v_lshlrev_b32_e32 v19, 16, v35
	v_pk_add_f32 v[12:13], v[18:19], v[16:17] op_sel:[1,0] op_sel_hi:[0,1]
	v_pk_add_f32 v[24:25], v[16:17], v[18:19] op_sel:[0,1] op_sel_hi:[1,0] neg_lo:[0,1] neg_hi:[0,1]
	v_pk_add_f32 v[22:23], v[18:19], 0 op_sel_hi:[1,0]
	v_mov_b32_e32 v27, v25
	v_pk_mov_b32 v[24:25], v[24:25], v[12:13] op_sel:[1,0]
	v_pk_add_f32 v[8:9], v[20:21], v[22:23]
	v_pk_mul_f32 v[24:25], v[14:15], v[24:25] op_sel_hi:[0,1]
	v_pk_add_f32 v[22:23], v[20:21], v[22:23] neg_lo:[0,1] neg_hi:[0,1]
	v_mov_b32_e32 v15, v10
	v_mov_b32_e32 v20, v14
	v_mov_b32_e32 v21, v11
	v_mov_b32_e32 v26, v12
	v_pk_mul_f32 v[20:21], v[14:15], v[20:21]
	v_pk_fma_f32 v[12:13], v[10:11], v[12:13], v[24:25]
	v_pk_fma_f32 v[24:25], v[10:11], v[26:27], v[24:25] op_sel_hi:[0,1,1] neg_lo:[0,0,1] neg_hi:[0,0,1]
	v_pk_fma_f32 v[26:27], v[10:11], v[10:11], v[20:21] op_sel_hi:[0,1,1] neg_lo:[0,0,1] neg_hi:[0,0,1]
	v_pk_fma_f32 v[20:21], v[10:11], v[10:11], v[20:21] op_sel_hi:[0,1,1]
	s_nop 0
	v_pk_mov_b32 v[30:31], v[20:21], v[26:27] op_sel:[1,0]
	v_mov_b32_e32 v28, v26
	v_mov_b32_e32 v29, v21
	v_pk_mul_f32 v[14:15], v[14:15], v[30:31] op_sel_hi:[0,1]
	s_nop 0
	v_pk_fma_f32 v[30:31], v[10:11], v[28:29], v[14:15] op_sel_hi:[0,1,1]
	v_pk_fma_f32 v[10:11], v[10:11], v[28:29], v[14:15] op_sel_hi:[0,1,1] neg_lo:[0,0,1] neg_hi:[0,0,1]
	s_nop 0
	v_mov_b32_e32 v15, v11
	v_sub_f32_e32 v24, v16, v19
	v_add_f32_e32 v16, v17, v18
	v_pk_mov_b32 v[10:11], v[10:11], v[30:31] op_sel:[1,0]
	v_mov_b32_e32 v14, v30
	v_pk_mul_f32 v[10:11], v[16:17], v[10:11] op_sel_hi:[0,1]
	s_nop 0
	v_pk_fma_f32 v[16:17], v[24:25], v[30:31], v[10:11] op_sel_hi:[0,1,1] neg_lo:[0,0,1] neg_hi:[0,0,1]
	v_pk_fma_f32 v[28:29], v[24:25], v[14:15], v[10:11] op_sel_hi:[0,1,1]
	v_pk_mul_f32 v[10:11], v[20:21], v[22:23] op_sel:[1,1] op_sel_hi:[1,0]
	v_and_b32_e32 v31, 0xffff0000, v33
	v_pk_fma_f32 v[20:21], v[26:27], v[22:23], v[10:11] neg_lo:[0,0,1] neg_hi:[0,0,1]
	v_pk_fma_f32 v[26:27], v[26:27], v[22:23], v[10:11] op_sel_hi:[0,1,1]
	v_add_u32_e32 v10, 1, v7
	v_cvt_f32_i32_e32 v10, v10
	v_and_b32_e32 v30, 0xffff0000, v32
	v_and_b32_e32 v33, 0xffff0000, v35
	v_and_b32_e32 v32, 0xffff0000, v34
	v_mul_f32_e32 v10, 0x38800000, v10
	v_sin_f32_e32 v22, v10
	v_pk_add_f32 v[34:35], v[30:31], 0 op_sel_hi:[1,0]
	v_pk_add_f32 v[36:37], v[32:33], 0 op_sel_hi:[1,0]
	v_cos_f32_e32 v18, v10
	v_pk_add_f32 v[10:11], v[34:35], v[36:37]
	ds_write_b128 v6, v[8:11]
	v_pk_add_f32 v[8:9], v[32:33], v[30:31] op_sel:[1,0] op_sel_hi:[0,1]
	v_pk_add_f32 v[10:11], v[30:31], v[32:33] op_sel:[0,1] op_sel_hi:[1,0] neg_lo:[0,1] neg_hi:[0,1]
	v_xor_b32_e32 v19, 0x80000000, v22
	v_mov_b32_e32 v39, v11
	v_pk_mov_b32 v[10:11], v[10:11], v[8:9] op_sel:[1,0]
	v_mov_b32_e32 v38, v8
	v_pk_mul_f32 v[10:11], v[22:23], v[10:11] op_sel_hi:[0,1]
	s_nop 0
	v_pk_fma_f32 v[14:15], v[18:19], v[8:9], v[10:11]
	v_pk_fma_f32 v[8:9], v[18:19], v[38:39], v[10:11] op_sel_hi:[0,1,1] neg_lo:[0,0,1] neg_hi:[0,0,1]
	v_mov_b32_e32 v23, v18
	v_mov_b32_e32 v10, v22
	v_mov_b32_e32 v11, v19
	v_mov_b32_e32 v13, v25
	v_mov_b32_e32 v15, v9
	v_pk_mul_f32 v[10:11], v[22:23], v[10:11]
	ds_write_b128 v6, v[12:15] offset:32768
	v_pk_fma_f32 v[12:13], v[18:19], v[18:19], v[10:11] op_sel_hi:[0,1,1] neg_lo:[0,0,1] neg_hi:[0,0,1]
	v_pk_fma_f32 v[10:11], v[18:19], v[18:19], v[10:11] op_sel_hi:[0,1,1]
	s_nop 0
	v_pk_mov_b32 v[24:25], v[10:11], v[12:13] op_sel:[1,0]
	v_mov_b32_e32 v14, v12
	v_mov_b32_e32 v15, v11
	v_pk_mul_f32 v[22:23], v[22:23], v[24:25] op_sel_hi:[0,1]
	s_nop 0
	v_pk_fma_f32 v[24:25], v[18:19], v[14:15], v[22:23] op_sel_hi:[0,1,1]
	v_pk_fma_f32 v[14:15], v[18:19], v[14:15], v[22:23] op_sel_hi:[0,1,1] neg_lo:[0,0,1] neg_hi:[0,0,1]
	v_pk_add_f32 v[8:9], v[34:35], v[36:37] neg_lo:[0,1] neg_hi:[0,1]
	v_mov_b32_e32 v23, v15
	v_pk_add_f32 v[18:19], v[30:31], v[32:33] op_sel:[1,0] op_sel_hi:[1,0]
	v_pk_mov_b32 v[14:15], v[14:15], v[24:25] op_sel:[1,0]
	v_mov_b32_e32 v22, v24
	v_pk_add_f32 v[34:35], v[30:31], v[32:33] op_sel:[0,1] op_sel_hi:[0,1] neg_lo:[0,1] neg_hi:[0,1]
	v_pk_mul_f32 v[14:15], v[18:19], v[14:15]
	v_pk_mul_f32 v[10:11], v[10:11], v[8:9] op_sel:[1,1] op_sel_hi:[1,0]
	v_pk_fma_f32 v[18:19], v[34:35], v[24:25], v[14:15] neg_lo:[0,0,1] neg_hi:[0,0,1]
	v_pk_fma_f32 v[14:15], v[34:35], v[22:23], v[14:15]
	v_pk_fma_f32 v[22:23], v[12:13], v[8:9], v[10:11] neg_lo:[0,0,1] neg_hi:[0,0,1]
	v_pk_fma_f32 v[8:9], v[12:13], v[8:9], v[10:11] op_sel_hi:[0,1,1]
	s_nop 0
	v_add_u32_e32 v8, 0x400, v7
	v_mov_b32_e32 v21, v27
	v_mov_b32_e32 v23, v9
	v_mov_b32_e32 v17, v29
	v_mov_b32_e32 v19, v15
	v_add_u32_e32 v6, 0x2000, v6
	v_mov_b32_e32 v7, v8
	ds_write_b128 v40, v[20:23]
	ds_write_b128 v41, v[16:19]
	s_nop 0
	s_mov_b64 s[12:13], exec
